# RWKV prompt job: chunk outputs handed to the staging waves through LDS (scan waves no longer convert/store them, except the last chunk)
# baseline (speedup 1.0000x reference)
.Lrw_stage2:
	s_cmp_lt_i32 s64, 1
	s_cbranch_scc1 .Lrw_st_nobr
	s_add_i32 s58, s64, -1
	s_and_b32 s59, s58, 1
	s_mul_i32 s59, s59, 0x1200
	s_add_u32 s59, s59, 0x19000
	v_readlane_b32 s70, v252, 60
	s_nop 3
	s_sub_i32 s70, s70, 32
	s_lshl_b32 s70, s70, 3
	v_add_u32_e32 v32, s70, v162
	v_lshrrev_b32_e32 v33, 3, v32
	v_and_b32_e32 v34, 7, v32
	v_mul_u32_u24_e32 v35, 0x90, v33
	v_lshl_add_u32 v35, v34, 4, v35
	v_add_u32_e32 v35, s59, v35
	ds_read_b128 v[36:39], v35
	s_lshl_b32 s58, s58, 5
	s_add_u32 s58, s58, s4
	v_add_u32_e32 v33, s58, v33
	v_mul_u32_u24_e32 v33, 0xc00, v33
	s_lshl_b32 s58, s28, 6
	v_lshl_add_u32 v34, v34, 3, s58
	v_add_u32_e32 v33, v33, v34
	s_waitcnt lgkmcnt(0)
	v_bfe_u32 v40, v36, 16, 1
	v_add3_u32 v36, v36, v40, s78
	v_bfe_u32 v40, v37, 16, 1
	v_add3_u32 v37, v37, v40, s78
	v_bfe_u32 v40, v38, 16, 1
	v_add3_u32 v38, v38, v40, s78
	v_bfe_u32 v40, v39, 16, 1
	v_add3_u32 v39, v39, v40, s78
	s_mov_b32 s58, 0x7060302
	v_perm_b32 v36, v37, v36, s58
	v_perm_b32 v37, v39, v38, s58
	global_store_dwordx2 v33, v[36:37], s[60:61]

.Lrw_fast:
	s_setprio 3
	s_and_b32 s89, s64, 1
	s_mul_i32 s89, s89, 0xc000
	v_lshl_add_u32 v112, s28, 5, v81
	v_lshl_add_u32 v124, v84, 2, s89
	v_lshl_add_u32 v135, v112, 2, s89
	ds_read_b128 v[76:79], v124 offset:272
	ds_read_b128 v[72:75], v124 offset:256
	ds_read_b128 v[68:71], v124 offset:512
	ds_read_b128 v[56:59], v124 offset:528
	ds_read_b32 v0, v135 offset:1280
	ds_read_b128 v[64:67], v124 offset:768
	ds_read_b128 v[60:63], v124 offset:784
	ds_read_b128 v[48:51], v124 offset:0
	ds_read_b128 v[40:43], v124 offset:16
	ds_read_b128 v[52:55], v124 offset:1040
	ds_read_b128 v[44:47], v124 offset:1024
	ds_read_b128 v[156:159], v124 offset:1808
	ds_read_b128 v[152:155], v124 offset:1792
	ds_read_b128 v[182:185], v124 offset:2048
	ds_read_b128 v[186:189], v124 offset:2064
	ds_read_b32 v160, v135 offset:2816
	ds_read_b128 v[190:193], v124 offset:2304
	ds_read_b128 v[194:197], v124 offset:2320
	ds_read_b128 v[144:147], v124 offset:1536
	ds_read_b128 v[148:151], v124 offset:1552
	ds_read_b128 v[202:205], v124 offset:2576
	ds_read_b128 v[198:201], v124 offset:2560
	s_waitcnt lgkmcnt(11)
	v_pk_mul_f32 v[76:77], v[32:33], v[76:77]
	v_pk_mul_f32 v[78:79], v[34:35], v[78:79]
	v_pk_fma_f32 v[72:73], v[36:37], v[72:73], v[76:77]
	v_pk_fma_f32 v[74:75], v[38:39], v[74:75], v[78:79]
	v_pk_add_f32 v[72:73], v[72:73], v[74:75]
	v_add_f32_e32 v142, v72, v73
	s_nop 1
	v_add_f32_dpp v142, v142, v142 quad_perm:[1,0,3,2] row_mask:0xf bank_mask:0xf bound_ctrl:1
	s_nop 1
	v_add_f32_dpp v142, v142, v142 quad_perm:[2,3,0,1] row_mask:0xf bank_mask:0xf bound_ctrl:1
	s_nop 1
	v_add_f32_dpp v142, v142, v142 row_half_mirror row_mask:0xf bank_mask:0xf bound_ctrl:1
	v_pk_mul_f32 v[68:69], v[68:69], v[142:143] op_sel_hi:[1,0]
	v_pk_mul_f32 v[70:71], v[70:71], v[142:143] op_sel_hi:[1,0]
	v_pk_mul_f32 v[56:57], v[56:57], v[142:143] op_sel_hi:[1,0]
	v_pk_mul_f32 v[58:59], v[58:59], v[142:143] op_sel_hi:[1,0]
	v_pk_fma_f32 v[64:65], v[64:65], v[0:1], v[68:69] op_sel_hi:[1,0,1] neg_lo:[0,0,1] neg_hi:[0,0,1]
	v_pk_fma_f32 v[66:67], v[66:67], v[0:1], v[70:71] op_sel_hi:[1,0,1] neg_lo:[0,0,1] neg_hi:[0,0,1]
	v_pk_fma_f32 v[60:61], v[60:61], v[0:1], v[56:57] op_sel_hi:[1,0,1] neg_lo:[0,0,1] neg_hi:[0,0,1]
	v_pk_fma_f32 v[62:63], v[62:63], v[0:1], v[58:59] op_sel_hi:[1,0,1] neg_lo:[0,0,1] neg_hi:[0,0,1]
	v_pk_fma_f32 v[36:37], v[36:37], v[48:49], v[64:65]
	v_pk_fma_f32 v[38:39], v[38:39], v[50:51], v[66:67]
	v_pk_fma_f32 v[32:33], v[32:33], v[40:41], v[60:61]
	v_pk_fma_f32 v[34:35], v[34:35], v[42:43], v[62:63]
	s_waitcnt lgkmcnt(2)
	v_pk_mul_f32 v[156:157], v[32:33], v[156:157]
	v_pk_mul_f32 v[52:53], v[32:33], v[52:53]
	v_pk_mul_f32 v[158:159], v[34:35], v[158:159]
	v_pk_mul_f32 v[54:55], v[34:35], v[54:55]
	v_pk_fma_f32 v[152:153], v[36:37], v[152:153], v[156:157]
	v_pk_fma_f32 v[44:45], v[36:37], v[44:45], v[52:53]
	v_pk_fma_f32 v[154:155], v[38:39], v[154:155], v[158:159]
	v_pk_fma_f32 v[46:47], v[38:39], v[46:47], v[54:55]
	v_pk_add_f32 v[152:153], v[152:153], v[154:155]
	v_pk_add_f32 v[44:45], v[44:45], v[46:47]
	v_add_f32_e32 v142, v152, v153
	v_add_f32_e32 v143, v44, v45
	ds_read_b128 v[76:79], v124 offset:3344
	v_add_f32_dpp v142, v142, v142 quad_perm:[1,0,3,2] row_mask:0xf bank_mask:0xf bound_ctrl:1
	v_add_f32_dpp v143, v143, v143 quad_perm:[1,0,3,2] row_mask:0xf bank_mask:0xf bound_ctrl:1
	ds_read_b128 v[72:75], v124 offset:3328
	v_add_f32_dpp v142, v142, v142 quad_perm:[2,3,0,1] row_mask:0xf bank_mask:0xf bound_ctrl:1
	v_add_f32_dpp v143, v143, v143 quad_perm:[2,3,0,1] row_mask:0xf bank_mask:0xf bound_ctrl:1
	ds_read_b128 v[68:71], v124 offset:3584
	v_add_f32_dpp v142, v142, v142 row_half_mirror row_mask:0xf bank_mask:0xf bound_ctrl:1
	v_add_f32_dpp v143, v143, v143 row_half_mirror row_mask:0xf bank_mask:0xf bound_ctrl:1
	ds_read_b128 v[56:59], v124 offset:3600
	ds_read_b32 v0, v135 offset:4352
	ds_read_b128 v[64:67], v124 offset:3840
	ds_read_b128 v[60:63], v124 offset:3856
	ds_read_b128 v[48:51], v124 offset:3072
	ds_read_b128 v[40:43], v124 offset:3088
	v_pk_mul_f32 v[182:183], v[182:183], v[142:143] op_sel_hi:[1,0]
	v_pk_mul_f32 v[184:185], v[184:185], v[142:143] op_sel_hi:[1,0]
	s_mov_b32 vcc_lo, 0x1010101
	v_pk_mul_f32 v[186:187], v[186:187], v[142:143] op_sel_hi:[1,0]
	v_pk_mul_f32 v[188:189], v[188:189], v[142:143] op_sel_hi:[1,0]
	s_mov_b32 vcc_hi, 0x1010101
	v_pk_fma_f32 v[190:191], v[190:191], v[160:161], v[182:183] op_sel_hi:[1,0,1] neg_lo:[0,0,1] neg_hi:[0,0,1]
	v_pk_fma_f32 v[192:193], v[192:193], v[160:161], v[184:185] op_sel_hi:[1,0,1] neg_lo:[0,0,1] neg_hi:[0,0,1]
	v_cndmask_b32_e32 v134, v134, v143, vcc
	v_pk_fma_f32 v[194:195], v[194:195], v[160:161], v[186:187] op_sel_hi:[1,0,1] neg_lo:[0,0,1] neg_hi:[0,0,1]
	v_pk_fma_f32 v[196:197], v[196:197], v[160:161], v[188:189] op_sel_hi:[1,0,1] neg_lo:[0,0,1] neg_hi:[0,0,1]
	ds_read_b128 v[52:55], v124 offset:4112
	ds_read_b128 v[44:47], v124 offset:4096
	v_pk_fma_f32 v[36:37], v[36:37], v[144:145], v[190:191]
	v_pk_fma_f32 v[38:39], v[38:39], v[146:147], v[192:193]
	v_pk_fma_f32 v[32:33], v[32:33], v[148:149], v[194:195]
	v_pk_fma_f32 v[34:35], v[34:35], v[150:151], v[196:197]
	s_waitcnt lgkmcnt(2)
	v_pk_mul_f32 v[76:77], v[32:33], v[76:77]
	v_pk_mul_f32 v[202:203], v[32:33], v[202:203]
	v_pk_mul_f32 v[78:79], v[34:35], v[78:79]
	v_pk_mul_f32 v[204:205], v[34:35], v[204:205]
	v_pk_fma_f32 v[72:73], v[36:37], v[72:73], v[76:77]
	v_pk_fma_f32 v[198:199], v[36:37], v[198:199], v[202:203]
	v_pk_fma_f32 v[74:75], v[38:39], v[74:75], v[78:79]
	v_pk_fma_f32 v[200:201], v[38:39], v[200:201], v[204:205]
	v_pk_add_f32 v[72:73], v[72:73], v[74:75]
	v_pk_add_f32 v[198:199], v[198:199], v[200:201]
	v_add_f32_e32 v142, v72, v73
	v_add_f32_e32 v143, v198, v199
	ds_read_b128 v[156:159], v124 offset:4880
	v_add_f32_dpp v142, v142, v142 quad_perm:[1,0,3,2] row_mask:0xf bank_mask:0xf bound_ctrl:1
	v_add_f32_dpp v143, v143, v143 quad_perm:[1,0,3,2] row_mask:0xf bank_mask:0xf bound_ctrl:1
	ds_read_b128 v[152:155], v124 offset:4864
	v_add_f32_dpp v142, v142, v142 quad_perm:[2,3,0,1] row_mask:0xf bank_mask:0xf bound_ctrl:1
	v_add_f32_dpp v143, v143, v143 quad_perm:[2,3,0,1] row_mask:0xf bank_mask:0xf bound_ctrl:1
	ds_read_b128 v[182:185], v124 offset:5120
	v_add_f32_dpp v142, v142, v142 row_half_mirror row_mask:0xf bank_mask:0xf bound_ctrl:1
	v_add_f32_dpp v143, v143, v143 row_half_mirror row_mask:0xf bank_mask:0xf bound_ctrl:1
	ds_read_b128 v[186:189], v124 offset:5136
	ds_read_b32 v160, v135 offset:5888
	ds_read_b128 v[190:193], v124 offset:5376
	ds_read_b128 v[194:197], v124 offset:5392
	ds_read_b128 v[144:147], v124 offset:4608
	ds_read_b128 v[148:151], v124 offset:4624
	v_pk_mul_f32 v[68:69], v[68:69], v[142:143] op_sel_hi:[1,0]
	v_pk_mul_f32 v[70:71], v[70:71], v[142:143] op_sel_hi:[1,0]
	s_lshl_b64 vcc, vcc, 1
	v_pk_mul_f32 v[56:57], v[56:57], v[142:143] op_sel_hi:[1,0]
	v_pk_mul_f32 v[58:59], v[58:59], v[142:143] op_sel_hi:[1,0]
	v_pk_fma_f32 v[64:65], v[64:65], v[0:1], v[68:69] op_sel_hi:[1,0,1] neg_lo:[0,0,1] neg_hi:[0,0,1]
	v_pk_fma_f32 v[66:67], v[66:67], v[0:1], v[70:71] op_sel_hi:[1,0,1] neg_lo:[0,0,1] neg_hi:[0,0,1]
	v_cndmask_b32_e32 v134, v134, v143, vcc
	v_pk_fma_f32 v[60:61], v[60:61], v[0:1], v[56:57] op_sel_hi:[1,0,1] neg_lo:[0,0,1] neg_hi:[0,0,1]
	v_pk_fma_f32 v[62:63], v[62:63], v[0:1], v[58:59] op_sel_hi:[1,0,1] neg_lo:[0,0,1] neg_hi:[0,0,1]
	ds_read_b128 v[202:205], v124 offset:5648
	ds_read_b128 v[198:201], v124 offset:5632
	v_pk_fma_f32 v[36:37], v[36:37], v[48:49], v[64:65]
	v_pk_fma_f32 v[38:39], v[38:39], v[50:51], v[66:67]
	v_pk_fma_f32 v[32:33], v[32:33], v[40:41], v[60:61]
	v_pk_fma_f32 v[34:35], v[34:35], v[42:43], v[62:63]
	s_waitcnt lgkmcnt(2)
	v_pk_mul_f32 v[156:157], v[32:33], v[156:157]
	v_pk_mul_f32 v[52:53], v[32:33], v[52:53]
	v_pk_mul_f32 v[158:159], v[34:35], v[158:159]
	v_pk_mul_f32 v[54:55], v[34:35], v[54:55]
	v_pk_fma_f32 v[152:153], v[36:37], v[152:153], v[156:157]
	v_pk_fma_f32 v[44:45], v[36:37], v[44:45], v[52:53]
	v_pk_fma_f32 v[154:155], v[38:39], v[154:155], v[158:159]
	v_pk_fma_f32 v[46:47], v[38:39], v[46:47], v[54:55]
	v_pk_add_f32 v[152:153], v[152:153], v[154:155]
	v_pk_add_f32 v[44:45], v[44:45], v[46:47]
	v_add_f32_e32 v142, v152, v153
	v_add_f32_e32 v143, v44, v45
	ds_read_b128 v[76:79], v124 offset:6416
	v_add_f32_dpp v142, v142, v142 quad_perm:[1,0,3,2] row_mask:0xf bank_mask:0xf bound_ctrl:1
	v_add_f32_dpp v143, v143, v143 quad_perm:[1,0,3,2] row_mask:0xf bank_mask:0xf bound_ctrl:1
	ds_read_b128 v[72:75], v124 offset:6400
	v_add_f32_dpp v142, v142, v142 quad_perm:[2,3,0,1] row_mask:0xf bank_mask:0xf bound_ctrl:1
	v_add_f32_dpp v143, v143, v143 quad_perm:[2,3,0,1] row_mask:0xf bank_mask:0xf bound_ctrl:1
	ds_read_b128 v[68:71], v124 offset:6656
	v_add_f32_dpp v142, v142, v142 row_half_mirror row_mask:0xf bank_mask:0xf bound_ctrl:1
	v_add_f32_dpp v143, v143, v143 row_half_mirror row_mask:0xf bank_mask:0xf bound_ctrl:1
	ds_read_b128 v[56:59], v124 offset:6672
	ds_read_b32 v0, v135 offset:7424
	ds_read_b128 v[64:67], v124 offset:6912
	ds_read_b128 v[60:63], v124 offset:6928
	ds_read_b128 v[48:51], v124 offset:6144
	ds_read_b128 v[40:43], v124 offset:6160
	v_pk_mul_f32 v[182:183], v[182:183], v[142:143] op_sel_hi:[1,0]
	v_pk_mul_f32 v[184:185], v[184:185], v[142:143] op_sel_hi:[1,0]
	s_lshl_b64 vcc, vcc, 1
	v_pk_mul_f32 v[186:187], v[186:187], v[142:143] op_sel_hi:[1,0]
	v_pk_mul_f32 v[188:189], v[188:189], v[142:143] op_sel_hi:[1,0]
	v_pk_fma_f32 v[190:191], v[190:191], v[160:161], v[182:183] op_sel_hi:[1,0,1] neg_lo:[0,0,1] neg_hi:[0,0,1]
	v_pk_fma_f32 v[192:193], v[192:193], v[160:161], v[184:185] op_sel_hi:[1,0,1] neg_lo:[0,0,1] neg_hi:[0,0,1]
	v_cndmask_b32_e32 v134, v134, v143, vcc
	v_pk_fma_f32 v[194:195], v[194:195], v[160:161], v[186:187] op_sel_hi:[1,0,1] neg_lo:[0,0,1] neg_hi:[0,0,1]
	v_pk_fma_f32 v[196:197], v[196:197], v[160:161], v[188:189] op_sel_hi:[1,0,1] neg_lo:[0,0,1] neg_hi:[0,0,1]
	ds_read_b128 v[52:55], v124 offset:7184
	ds_read_b128 v[44:47], v124 offset:7168
	v_pk_fma_f32 v[36:37], v[36:37], v[144:145], v[190:191]
	v_pk_fma_f32 v[38:39], v[38:39], v[146:147], v[192:193]
	v_pk_fma_f32 v[32:33], v[32:33], v[148:149], v[194:195]
	v_pk_fma_f32 v[34:35], v[34:35], v[150:151], v[196:197]
	s_waitcnt lgkmcnt(2)
	v_pk_mul_f32 v[76:77], v[32:33], v[76:77]
	v_pk_mul_f32 v[202:203], v[32:33], v[202:203]
	v_pk_mul_f32 v[78:79], v[34:35], v[78:79]
	v_pk_mul_f32 v[204:205], v[34:35], v[204:205]
	v_pk_fma_f32 v[72:73], v[36:37], v[72:73], v[76:77]
	v_pk_fma_f32 v[198:199], v[36:37], v[198:199], v[202:203]
	v_pk_fma_f32 v[74:75], v[38:39], v[74:75], v[78:79]
	v_pk_fma_f32 v[200:201], v[38:39], v[200:201], v[204:205]
	v_pk_add_f32 v[72:73], v[72:73], v[74:75]
	v_pk_add_f32 v[198:199], v[198:199], v[200:201]
	v_add_f32_e32 v142, v72, v73
	v_add_f32_e32 v143, v198, v199
	ds_read_b128 v[156:159], v124 offset:7952
	v_add_f32_dpp v142, v142, v142 quad_perm:[1,0,3,2] row_mask:0xf bank_mask:0xf bound_ctrl:1
	v_add_f32_dpp v143, v143, v143 quad_perm:[1,0,3,2] row_mask:0xf bank_mask:0xf bound_ctrl:1
	ds_read_b128 v[152:155], v124 offset:7936
	v_add_f32_dpp v142, v142, v142 quad_perm:[2,3,0,1] row_mask:0xf bank_mask:0xf bound_ctrl:1
	v_add_f32_dpp v143, v143, v143 quad_perm:[2,3,0,1] row_mask:0xf bank_mask:0xf bound_ctrl:1
	ds_read_b128 v[182:185], v124 offset:8192
	v_add_f32_dpp v142, v142, v142 row_half_mirror row_mask:0xf bank_mask:0xf bound_ctrl:1
	v_add_f32_dpp v143, v143, v143 row_half_mirror row_mask:0xf bank_mask:0xf bound_ctrl:1
	ds_read_b128 v[186:189], v124 offset:8208
	ds_read_b32 v160, v135 offset:8960
	ds_read_b128 v[190:193], v124 offset:8448
	ds_read_b128 v[194:197], v124 offset:8464
	ds_read_b128 v[144:147], v124 offset:7680
	ds_read_b128 v[148:151], v124 offset:7696
	v_pk_mul_f32 v[68:69], v[68:69], v[142:143] op_sel_hi:[1,0]
	v_pk_mul_f32 v[70:71], v[70:71], v[142:143] op_sel_hi:[1,0]
	s_lshl_b64 vcc, vcc, 1
	v_pk_mul_f32 v[56:57], v[56:57], v[142:143] op_sel_hi:[1,0]
	v_pk_mul_f32 v[58:59], v[58:59], v[142:143] op_sel_hi:[1,0]
	v_pk_fma_f32 v[64:65], v[64:65], v[0:1], v[68:69] op_sel_hi:[1,0,1] neg_lo:[0,0,1] neg_hi:[0,0,1]
	v_pk_fma_f32 v[66:67], v[66:67], v[0:1], v[70:71] op_sel_hi:[1,0,1] neg_lo:[0,0,1] neg_hi:[0,0,1]
	v_cndmask_b32_e32 v134, v134, v143, vcc
	v_pk_fma_f32 v[60:61], v[60:61], v[0:1], v[56:57] op_sel_hi:[1,0,1] neg_lo:[0,0,1] neg_hi:[0,0,1]
	v_pk_fma_f32 v[62:63], v[62:63], v[0:1], v[58:59] op_sel_hi:[1,0,1] neg_lo:[0,0,1] neg_hi:[0,0,1]
	ds_read_b128 v[202:205], v124 offset:8720
	ds_read_b128 v[198:201], v124 offset:8704
	v_pk_fma_f32 v[36:37], v[36:37], v[48:49], v[64:65]
	v_pk_fma_f32 v[38:39], v[38:39], v[50:51], v[66:67]
	v_pk_fma_f32 v[32:33], v[32:33], v[40:41], v[60:61]
	v_pk_fma_f32 v[34:35], v[34:35], v[42:43], v[62:63]
	s_waitcnt lgkmcnt(2)
	v_pk_mul_f32 v[156:157], v[32:33], v[156:157]
	v_pk_mul_f32 v[52:53], v[32:33], v[52:53]
	v_pk_mul_f32 v[158:159], v[34:35], v[158:159]
	v_pk_mul_f32 v[54:55], v[34:35], v[54:55]
	v_pk_fma_f32 v[152:153], v[36:37], v[152:153], v[156:157]
	v_pk_fma_f32 v[44:45], v[36:37], v[44:45], v[52:53]
	v_pk_fma_f32 v[154:155], v[38:39], v[154:155], v[158:159]
	v_pk_fma_f32 v[46:47], v[38:39], v[46:47], v[54:55]
	v_pk_add_f32 v[152:153], v[152:153], v[154:155]
	v_pk_add_f32 v[44:45], v[44:45], v[46:47]
	v_add_f32_e32 v142, v152, v153
	v_add_f32_e32 v143, v44, v45
	ds_read_b128 v[76:79], v124 offset:9488
	v_add_f32_dpp v142, v142, v142 quad_perm:[1,0,3,2] row_mask:0xf bank_mask:0xf bound_ctrl:1
	v_add_f32_dpp v143, v143, v143 quad_perm:[1,0,3,2] row_mask:0xf bank_mask:0xf bound_ctrl:1
	ds_read_b128 v[72:75], v124 offset:9472
	v_add_f32_dpp v142, v142, v142 quad_perm:[2,3,0,1] row_mask:0xf bank_mask:0xf bound_ctrl:1
	v_add_f32_dpp v143, v143, v143 quad_perm:[2,3,0,1] row_mask:0xf bank_mask:0xf bound_ctrl:1
	ds_read_b128 v[68:71], v124 offset:9728
	v_add_f32_dpp v142, v142, v142 row_half_mirror row_mask:0xf bank_mask:0xf bound_ctrl:1
	v_add_f32_dpp v143, v143, v143 row_half_mirror row_mask:0xf bank_mask:0xf bound_ctrl:1
	ds_read_b128 v[56:59], v124 offset:9744
	ds_read_b32 v0, v135 offset:10496
	ds_read_b128 v[64:67], v124 offset:9984
	ds_read_b128 v[60:63], v124 offset:10000
	ds_read_b128 v[48:51], v124 offset:9216
	ds_read_b128 v[40:43], v124 offset:9232
	v_pk_mul_f32 v[182:183], v[182:183], v[142:143] op_sel_hi:[1,0]
	v_pk_mul_f32 v[184:185], v[184:185], v[142:143] op_sel_hi:[1,0]
	s_lshl_b64 vcc, vcc, 1
	v_pk_mul_f32 v[186:187], v[186:187], v[142:143] op_sel_hi:[1,0]
	v_pk_mul_f32 v[188:189], v[188:189], v[142:143] op_sel_hi:[1,0]
	v_pk_fma_f32 v[190:191], v[190:191], v[160:161], v[182:183] op_sel_hi:[1,0,1] neg_lo:[0,0,1] neg_hi:[0,0,1]
	v_pk_fma_f32 v[192:193], v[192:193], v[160:161], v[184:185] op_sel_hi:[1,0,1] neg_lo:[0,0,1] neg_hi:[0,0,1]
	v_cndmask_b32_e32 v134, v134, v143, vcc
	v_pk_fma_f32 v[194:195], v[194:195], v[160:161], v[186:187] op_sel_hi:[1,0,1] neg_lo:[0,0,1] neg_hi:[0,0,1]
	v_pk_fma_f32 v[196:197], v[196:197], v[160:161], v[188:189] op_sel_hi:[1,0,1] neg_lo:[0,0,1] neg_hi:[0,0,1]
	ds_read_b128 v[52:55], v124 offset:10256
	ds_read_b128 v[44:47], v124 offset:10240
	v_pk_fma_f32 v[36:37], v[36:37], v[144:145], v[190:191]
	v_pk_fma_f32 v[38:39], v[38:39], v[146:147], v[192:193]
	v_pk_fma_f32 v[32:33], v[32:33], v[148:149], v[194:195]
	v_pk_fma_f32 v[34:35], v[34:35], v[150:151], v[196:197]
	s_waitcnt lgkmcnt(2)
	v_pk_mul_f32 v[76:77], v[32:33], v[76:77]
	v_pk_mul_f32 v[202:203], v[32:33], v[202:203]
	v_pk_mul_f32 v[78:79], v[34:35], v[78:79]
	v_pk_mul_f32 v[204:205], v[34:35], v[204:205]
	v_pk_fma_f32 v[72:73], v[36:37], v[72:73], v[76:77]
	v_pk_fma_f32 v[198:199], v[36:37], v[198:199], v[202:203]
	v_pk_fma_f32 v[74:75], v[38:39], v[74:75], v[78:79]
	v_pk_fma_f32 v[200:201], v[38:39], v[200:201], v[204:205]
	v_pk_add_f32 v[72:73], v[72:73], v[74:75]
	v_pk_add_f32 v[198:199], v[198:199], v[200:201]
	v_add_f32_e32 v142, v72, v73
	v_add_f32_e32 v143, v198, v199
	ds_read_b128 v[156:159], v124 offset:11024
	v_add_f32_dpp v142, v142, v142 quad_perm:[1,0,3,2] row_mask:0xf bank_mask:0xf bound_ctrl:1
	v_add_f32_dpp v143, v143, v143 quad_perm:[1,0,3,2] row_mask:0xf bank_mask:0xf bound_ctrl:1
	ds_read_b128 v[152:155], v124 offset:11008
	v_add_f32_dpp v142, v142, v142 quad_perm:[2,3,0,1] row_mask:0xf bank_mask:0xf bound_ctrl:1
	v_add_f32_dpp v143, v143, v143 quad_perm:[2,3,0,1] row_mask:0xf bank_mask:0xf bound_ctrl:1
	ds_read_b128 v[182:185], v124 offset:11264
	v_add_f32_dpp v142, v142, v142 row_half_mirror row_mask:0xf bank_mask:0xf bound_ctrl:1
	v_add_f32_dpp v143, v143, v143 row_half_mirror row_mask:0xf bank_mask:0xf bound_ctrl:1
	ds_read_b128 v[186:189], v124 offset:11280
	ds_read_b32 v160, v135 offset:12032
	ds_read_b128 v[190:193], v124 offset:11520
	ds_read_b128 v[194:197], v124 offset:11536
	ds_read_b128 v[144:147], v124 offset:10752
	ds_read_b128 v[148:151], v124 offset:10768
	v_pk_mul_f32 v[68:69], v[68:69], v[142:143] op_sel_hi:[1,0]
	v_pk_mul_f32 v[70:71], v[70:71], v[142:143] op_sel_hi:[1,0]
	s_lshl_b64 vcc, vcc, 1
	v_pk_mul_f32 v[56:57], v[56:57], v[142:143] op_sel_hi:[1,0]
	v_pk_mul_f32 v[58:59], v[58:59], v[142:143] op_sel_hi:[1,0]
	v_pk_fma_f32 v[64:65], v[64:65], v[0:1], v[68:69] op_sel_hi:[1,0,1] neg_lo:[0,0,1] neg_hi:[0,0,1]
	v_pk_fma_f32 v[66:67], v[66:67], v[0:1], v[70:71] op_sel_hi:[1,0,1] neg_lo:[0,0,1] neg_hi:[0,0,1]
	v_cndmask_b32_e32 v134, v134, v143, vcc
	v_pk_fma_f32 v[60:61], v[60:61], v[0:1], v[56:57] op_sel_hi:[1,0,1] neg_lo:[0,0,1] neg_hi:[0,0,1]
	v_pk_fma_f32 v[62:63], v[62:63], v[0:1], v[58:59] op_sel_hi:[1,0,1] neg_lo:[0,0,1] neg_hi:[0,0,1]
	ds_read_b128 v[202:205], v124 offset:11792
	ds_read_b128 v[198:201], v124 offset:11776
	v_pk_fma_f32 v[36:37], v[36:37], v[48:49], v[64:65]
	v_pk_fma_f32 v[38:39], v[38:39], v[50:51], v[66:67]
	v_pk_fma_f32 v[32:33], v[32:33], v[40:41], v[60:61]
	v_pk_fma_f32 v[34:35], v[34:35], v[42:43], v[62:63]
	s_waitcnt lgkmcnt(2)
	v_pk_mul_f32 v[156:157], v[32:33], v[156:157]
	v_pk_mul_f32 v[52:53], v[32:33], v[52:53]
	v_pk_mul_f32 v[158:159], v[34:35], v[158:159]
	v_pk_mul_f32 v[54:55], v[34:35], v[54:55]
	v_pk_fma_f32 v[152:153], v[36:37], v[152:153], v[156:157]
	v_pk_fma_f32 v[44:45], v[36:37], v[44:45], v[52:53]
	v_pk_fma_f32 v[154:155], v[38:39], v[154:155], v[158:159]
	v_pk_fma_f32 v[46:47], v[38:39], v[46:47], v[54:55]
	v_pk_add_f32 v[152:153], v[152:153], v[154:155]
	v_pk_add_f32 v[44:45], v[44:45], v[46:47]
	v_add_f32_e32 v142, v152, v153
	v_add_f32_e32 v143, v44, v45
	ds_read_b128 v[76:79], v124 offset:12560
	v_add_f32_dpp v142, v142, v142 quad_perm:[1,0,3,2] row_mask:0xf bank_mask:0xf bound_ctrl:1
	v_add_f32_dpp v143, v143, v143 quad_perm:[1,0,3,2] row_mask:0xf bank_mask:0xf bound_ctrl:1
	ds_read_b128 v[72:75], v124 offset:12544
	v_add_f32_dpp v142, v142, v142 quad_perm:[2,3,0,1] row_mask:0xf bank_mask:0xf bound_ctrl:1
	v_add_f32_dpp v143, v143, v143 quad_perm:[2,3,0,1] row_mask:0xf bank_mask:0xf bound_ctrl:1
	ds_read_b128 v[68:71], v124 offset:12800
	v_add_f32_dpp v142, v142, v142 row_half_mirror row_mask:0xf bank_mask:0xf bound_ctrl:1
	v_add_f32_dpp v143, v143, v143 row_half_mirror row_mask:0xf bank_mask:0xf bound_ctrl:1
	ds_read_b128 v[56:59], v124 offset:12816
	ds_read_b32 v0, v135 offset:13568
	ds_read_b128 v[64:67], v124 offset:13056
	ds_read_b128 v[60:63], v124 offset:13072
	ds_read_b128 v[48:51], v124 offset:12288
	ds_read_b128 v[40:43], v124 offset:12304
	v_pk_mul_f32 v[182:183], v[182:183], v[142:143] op_sel_hi:[1,0]
	v_pk_mul_f32 v[184:185], v[184:185], v[142:143] op_sel_hi:[1,0]
	s_lshl_b64 vcc, vcc, 1
	v_pk_mul_f32 v[186:187], v[186:187], v[142:143] op_sel_hi:[1,0]
	v_pk_mul_f32 v[188:189], v[188:189], v[142:143] op_sel_hi:[1,0]
	v_pk_fma_f32 v[190:191], v[190:191], v[160:161], v[182:183] op_sel_hi:[1,0,1] neg_lo:[0,0,1] neg_hi:[0,0,1]
	v_pk_fma_f32 v[192:193], v[192:193], v[160:161], v[184:185] op_sel_hi:[1,0,1] neg_lo:[0,0,1] neg_hi:[0,0,1]
	v_cndmask_b32_e32 v134, v134, v143, vcc
	v_pk_fma_f32 v[194:195], v[194:195], v[160:161], v[186:187] op_sel_hi:[1,0,1] neg_lo:[0,0,1] neg_hi:[0,0,1]
	v_pk_fma_f32 v[196:197], v[196:197], v[160:161], v[188:189] op_sel_hi:[1,0,1] neg_lo:[0,0,1] neg_hi:[0,0,1]
	ds_read_b128 v[52:55], v124 offset:13328
	ds_read_b128 v[44:47], v124 offset:13312
	v_pk_fma_f32 v[36:37], v[36:37], v[144:145], v[190:191]
	v_pk_fma_f32 v[38:39], v[38:39], v[146:147], v[192:193]
	v_pk_fma_f32 v[32:33], v[32:33], v[148:149], v[194:195]
	v_pk_fma_f32 v[34:35], v[34:35], v[150:151], v[196:197]
	s_waitcnt lgkmcnt(2)
	v_pk_mul_f32 v[76:77], v[32:33], v[76:77]
	v_pk_mul_f32 v[202:203], v[32:33], v[202:203]
	v_pk_mul_f32 v[78:79], v[34:35], v[78:79]
	v_pk_mul_f32 v[204:205], v[34:35], v[204:205]
	v_pk_fma_f32 v[72:73], v[36:37], v[72:73], v[76:77]
	v_pk_fma_f32 v[198:199], v[36:37], v[198:199], v[202:203]
	v_pk_fma_f32 v[74:75], v[38:39], v[74:75], v[78:79]
	v_pk_fma_f32 v[200:201], v[38:39], v[200:201], v[204:205]
	v_pk_add_f32 v[72:73], v[72:73], v[74:75]
	v_pk_add_f32 v[198:199], v[198:199], v[200:201]
	v_add_f32_e32 v142, v72, v73
	v_add_f32_e32 v143, v198, v199
	ds_read_b128 v[156:159], v124 offset:14096
	v_add_f32_dpp v142, v142, v142 quad_perm:[1,0,3,2] row_mask:0xf bank_mask:0xf bound_ctrl:1
	v_add_f32_dpp v143, v143, v143 quad_perm:[1,0,3,2] row_mask:0xf bank_mask:0xf bound_ctrl:1
	ds_read_b128 v[152:155], v124 offset:14080
	v_add_f32_dpp v142, v142, v142 quad_perm:[2,3,0,1] row_mask:0xf bank_mask:0xf bound_ctrl:1
	v_add_f32_dpp v143, v143, v143 quad_perm:[2,3,0,1] row_mask:0xf bank_mask:0xf bound_ctrl:1
	ds_read_b128 v[182:185], v124 offset:14336
	v_add_f32_dpp v142, v142, v142 row_half_mirror row_mask:0xf bank_mask:0xf bound_ctrl:1
	v_add_f32_dpp v143, v143, v143 row_half_mirror row_mask:0xf bank_mask:0xf bound_ctrl:1
	ds_read_b128 v[186:189], v124 offset:14352
	ds_read_b32 v160, v135 offset:15104
	ds_read_b128 v[190:193], v124 offset:14592
	ds_read_b128 v[194:197], v124 offset:14608
	ds_read_b128 v[144:147], v124 offset:13824
	ds_read_b128 v[148:151], v124 offset:13840
	v_pk_mul_f32 v[68:69], v[68:69], v[142:143] op_sel_hi:[1,0]
	v_pk_mul_f32 v[70:71], v[70:71], v[142:143] op_sel_hi:[1,0]
	s_lshl_b64 vcc, vcc, 1
	v_pk_mul_f32 v[56:57], v[56:57], v[142:143] op_sel_hi:[1,0]
	v_pk_mul_f32 v[58:59], v[58:59], v[142:143] op_sel_hi:[1,0]
	v_pk_fma_f32 v[64:65], v[64:65], v[0:1], v[68:69] op_sel_hi:[1,0,1] neg_lo:[0,0,1] neg_hi:[0,0,1]
	v_pk_fma_f32 v[66:67], v[66:67], v[0:1], v[70:71] op_sel_hi:[1,0,1] neg_lo:[0,0,1] neg_hi:[0,0,1]
	v_cndmask_b32_e32 v134, v134, v143, vcc
	v_pk_fma_f32 v[60:61], v[60:61], v[0:1], v[56:57] op_sel_hi:[1,0,1] neg_lo:[0,0,1] neg_hi:[0,0,1]
	v_pk_fma_f32 v[62:63], v[62:63], v[0:1], v[58:59] op_sel_hi:[1,0,1] neg_lo:[0,0,1] neg_hi:[0,0,1]
	ds_read_b128 v[202:205], v124 offset:14864
	ds_read_b128 v[198:201], v124 offset:14848
	v_pk_fma_f32 v[36:37], v[36:37], v[48:49], v[64:65]
	v_pk_fma_f32 v[38:39], v[38:39], v[50:51], v[66:67]
	v_pk_fma_f32 v[32:33], v[32:33], v[40:41], v[60:61]
	v_pk_fma_f32 v[34:35], v[34:35], v[42:43], v[62:63]
	s_waitcnt lgkmcnt(2)
	v_pk_mul_f32 v[156:157], v[32:33], v[156:157]
	v_pk_mul_f32 v[52:53], v[32:33], v[52:53]
	v_pk_mul_f32 v[158:159], v[34:35], v[158:159]
	v_pk_mul_f32 v[54:55], v[34:35], v[54:55]
	v_pk_fma_f32 v[152:153], v[36:37], v[152:153], v[156:157]
	v_pk_fma_f32 v[44:45], v[36:37], v[44:45], v[52:53]
	v_pk_fma_f32 v[154:155], v[38:39], v[154:155], v[158:159]
	v_pk_fma_f32 v[46:47], v[38:39], v[46:47], v[54:55]
	v_pk_add_f32 v[152:153], v[152:153], v[154:155]
	v_pk_add_f32 v[44:45], v[44:45], v[46:47]
	v_add_f32_e32 v142, v152, v153
	v_add_f32_e32 v143, v44, v45
	ds_read_b128 v[76:79], v124 offset:15632
	v_add_f32_dpp v142, v142, v142 quad_perm:[1,0,3,2] row_mask:0xf bank_mask:0xf bound_ctrl:1
	v_add_f32_dpp v143, v143, v143 quad_perm:[1,0,3,2] row_mask:0xf bank_mask:0xf bound_ctrl:1
	ds_read_b128 v[72:75], v124 offset:15616
	v_add_f32_dpp v142, v142, v142 quad_perm:[2,3,0,1] row_mask:0xf bank_mask:0xf bound_ctrl:1
	v_add_f32_dpp v143, v143, v143 quad_perm:[2,3,0,1] row_mask:0xf bank_mask:0xf bound_ctrl:1
	ds_read_b128 v[68:71], v124 offset:15872
	v_add_f32_dpp v142, v142, v142 row_half_mirror row_mask:0xf bank_mask:0xf bound_ctrl:1
	v_add_f32_dpp v143, v143, v143 row_half_mirror row_mask:0xf bank_mask:0xf bound_ctrl:1
	ds_read_b128 v[56:59], v124 offset:15888
	ds_read_b32 v0, v135 offset:16640
	ds_read_b128 v[64:67], v124 offset:16128
	ds_read_b128 v[60:63], v124 offset:16144
	ds_read_b128 v[48:51], v124 offset:15360
	ds_read_b128 v[40:43], v124 offset:15376
	v_pk_mul_f32 v[182:183], v[182:183], v[142:143] op_sel_hi:[1,0]
	v_pk_mul_f32 v[184:185], v[184:185], v[142:143] op_sel_hi:[1,0]
	s_mov_b32 vcc_lo, 0x1010101
	v_pk_mul_f32 v[186:187], v[186:187], v[142:143] op_sel_hi:[1,0]
	v_pk_mul_f32 v[188:189], v[188:189], v[142:143] op_sel_hi:[1,0]
	s_mov_b32 vcc_hi, 0x1010101
	v_pk_fma_f32 v[190:191], v[190:191], v[160:161], v[182:183] op_sel_hi:[1,0,1] neg_lo:[0,0,1] neg_hi:[0,0,1]
	v_pk_fma_f32 v[192:193], v[192:193], v[160:161], v[184:185] op_sel_hi:[1,0,1] neg_lo:[0,0,1] neg_hi:[0,0,1]
	v_cndmask_b32_e32 v133, v133, v143, vcc
	v_pk_fma_f32 v[194:195], v[194:195], v[160:161], v[186:187] op_sel_hi:[1,0,1] neg_lo:[0,0,1] neg_hi:[0,0,1]
	v_pk_fma_f32 v[196:197], v[196:197], v[160:161], v[188:189] op_sel_hi:[1,0,1] neg_lo:[0,0,1] neg_hi:[0,0,1]
	ds_read_b128 v[52:55], v124 offset:16400
	ds_read_b128 v[44:47], v124 offset:16384
	v_pk_fma_f32 v[36:37], v[36:37], v[144:145], v[190:191]
	v_pk_fma_f32 v[38:39], v[38:39], v[146:147], v[192:193]
	v_pk_fma_f32 v[32:33], v[32:33], v[148:149], v[194:195]
	v_pk_fma_f32 v[34:35], v[34:35], v[150:151], v[196:197]
	s_waitcnt lgkmcnt(2)
	v_pk_mul_f32 v[76:77], v[32:33], v[76:77]
	v_pk_mul_f32 v[202:203], v[32:33], v[202:203]
	v_pk_mul_f32 v[78:79], v[34:35], v[78:79]
	v_pk_mul_f32 v[204:205], v[34:35], v[204:205]
	v_pk_fma_f32 v[72:73], v[36:37], v[72:73], v[76:77]
	v_pk_fma_f32 v[198:199], v[36:37], v[198:199], v[202:203]
	v_pk_fma_f32 v[74:75], v[38:39], v[74:75], v[78:79]
	v_pk_fma_f32 v[200:201], v[38:39], v[200:201], v[204:205]
	v_pk_add_f32 v[72:73], v[72:73], v[74:75]
	v_pk_add_f32 v[198:199], v[198:199], v[200:201]
	v_add_f32_e32 v142, v72, v73
	v_add_f32_e32 v143, v198, v199
	ds_read_b128 v[156:159], v124 offset:17168
	v_add_f32_dpp v142, v142, v142 quad_perm:[1,0,3,2] row_mask:0xf bank_mask:0xf bound_ctrl:1
	v_add_f32_dpp v143, v143, v143 quad_perm:[1,0,3,2] row_mask:0xf bank_mask:0xf bound_ctrl:1
	ds_read_b128 v[152:155], v124 offset:17152
	v_add_f32_dpp v142, v142, v142 quad_perm:[2,3,0,1] row_mask:0xf bank_mask:0xf bound_ctrl:1
	v_add_f32_dpp v143, v143, v143 quad_perm:[2,3,0,1] row_mask:0xf bank_mask:0xf bound_ctrl:1
	ds_read_b128 v[182:185], v124 offset:17408
	v_add_f32_dpp v142, v142, v142 row_half_mirror row_mask:0xf bank_mask:0xf bound_ctrl:1
	v_add_f32_dpp v143, v143, v143 row_half_mirror row_mask:0xf bank_mask:0xf bound_ctrl:1
	ds_read_b128 v[186:189], v124 offset:17424
	ds_read_b32 v160, v135 offset:18176
	ds_read_b128 v[190:193], v124 offset:17664
	ds_read_b128 v[194:197], v124 offset:17680
	ds_read_b128 v[144:147], v124 offset:16896
	ds_read_b128 v[148:151], v124 offset:16912
	v_pk_mul_f32 v[68:69], v[68:69], v[142:143] op_sel_hi:[1,0]
	v_pk_mul_f32 v[70:71], v[70:71], v[142:143] op_sel_hi:[1,0]
	s_lshl_b64 vcc, vcc, 1
	v_pk_mul_f32 v[56:57], v[56:57], v[142:143] op_sel_hi:[1,0]
	v_pk_mul_f32 v[58:59], v[58:59], v[142:143] op_sel_hi:[1,0]
	v_pk_fma_f32 v[64:65], v[64:65], v[0:1], v[68:69] op_sel_hi:[1,0,1] neg_lo:[0,0,1] neg_hi:[0,0,1]
	v_pk_fma_f32 v[66:67], v[66:67], v[0:1], v[70:71] op_sel_hi:[1,0,1] neg_lo:[0,0,1] neg_hi:[0,0,1]
	v_cndmask_b32_e32 v133, v133, v143, vcc
	v_pk_fma_f32 v[60:61], v[60:61], v[0:1], v[56:57] op_sel_hi:[1,0,1] neg_lo:[0,0,1] neg_hi:[0,0,1]
	v_pk_fma_f32 v[62:63], v[62:63], v[0:1], v[58:59] op_sel_hi:[1,0,1] neg_lo:[0,0,1] neg_hi:[0,0,1]
	ds_read_b128 v[202:205], v124 offset:17936
	ds_read_b128 v[198:201], v124 offset:17920
	v_pk_fma_f32 v[36:37], v[36:37], v[48:49], v[64:65]
	v_pk_fma_f32 v[38:39], v[38:39], v[50:51], v[66:67]
	v_pk_fma_f32 v[32:33], v[32:33], v[40:41], v[60:61]
	v_pk_fma_f32 v[34:35], v[34:35], v[42:43], v[62:63]
	s_waitcnt lgkmcnt(2)
	v_pk_mul_f32 v[156:157], v[32:33], v[156:157]
	v_pk_mul_f32 v[52:53], v[32:33], v[52:53]
	v_pk_mul_f32 v[158:159], v[34:35], v[158:159]
	v_pk_mul_f32 v[54:55], v[34:35], v[54:55]
	v_pk_fma_f32 v[152:153], v[36:37], v[152:153], v[156:157]
	v_pk_fma_f32 v[44:45], v[36:37], v[44:45], v[52:53]
	v_pk_fma_f32 v[154:155], v[38:39], v[154:155], v[158:159]
	v_pk_fma_f32 v[46:47], v[38:39], v[46:47], v[54:55]
	v_pk_add_f32 v[152:153], v[152:153], v[154:155]
	v_pk_add_f32 v[44:45], v[44:45], v[46:47]
	v_add_f32_e32 v142, v152, v153
	v_add_f32_e32 v143, v44, v45
	ds_read_b128 v[76:79], v124 offset:18704
	v_add_f32_dpp v142, v142, v142 quad_perm:[1,0,3,2] row_mask:0xf bank_mask:0xf bound_ctrl:1
	v_add_f32_dpp v143, v143, v143 quad_perm:[1,0,3,2] row_mask:0xf bank_mask:0xf bound_ctrl:1
	ds_read_b128 v[72:75], v124 offset:18688
	v_add_f32_dpp v142, v142, v142 quad_perm:[2,3,0,1] row_mask:0xf bank_mask:0xf bound_ctrl:1
	v_add_f32_dpp v143, v143, v143 quad_perm:[2,3,0,1] row_mask:0xf bank_mask:0xf bound_ctrl:1
	ds_read_b128 v[68:71], v124 offset:18944
	v_add_f32_dpp v142, v142, v142 row_half_mirror row_mask:0xf bank_mask:0xf bound_ctrl:1
	v_add_f32_dpp v143, v143, v143 row_half_mirror row_mask:0xf bank_mask:0xf bound_ctrl:1
	ds_read_b128 v[56:59], v124 offset:18960
	ds_read_b32 v0, v135 offset:19712
	ds_read_b128 v[64:67], v124 offset:19200
	ds_read_b128 v[60:63], v124 offset:19216
	ds_read_b128 v[48:51], v124 offset:18432
	ds_read_b128 v[40:43], v124 offset:18448
	v_pk_mul_f32 v[182:183], v[182:183], v[142:143] op_sel_hi:[1,0]
	v_pk_mul_f32 v[184:185], v[184:185], v[142:143] op_sel_hi:[1,0]
	s_lshl_b64 vcc, vcc, 1
	v_pk_mul_f32 v[186:187], v[186:187], v[142:143] op_sel_hi:[1,0]
	v_pk_mul_f32 v[188:189], v[188:189], v[142:143] op_sel_hi:[1,0]
	v_pk_fma_f32 v[190:191], v[190:191], v[160:161], v[182:183] op_sel_hi:[1,0,1] neg_lo:[0,0,1] neg_hi:[0,0,1]
	v_pk_fma_f32 v[192:193], v[192:193], v[160:161], v[184:185] op_sel_hi:[1,0,1] neg_lo:[0,0,1] neg_hi:[0,0,1]
	v_cndmask_b32_e32 v133, v133, v143, vcc
	v_pk_fma_f32 v[194:195], v[194:195], v[160:161], v[186:187] op_sel_hi:[1,0,1] neg_lo:[0,0,1] neg_hi:[0,0,1]
	v_pk_fma_f32 v[196:197], v[196:197], v[160:161], v[188:189] op_sel_hi:[1,0,1] neg_lo:[0,0,1] neg_hi:[0,0,1]
	ds_read_b128 v[52:55], v124 offset:19472
	ds_read_b128 v[44:47], v124 offset:19456
	v_pk_fma_f32 v[36:37], v[36:37], v[144:145], v[190:191]
	v_pk_fma_f32 v[38:39], v[38:39], v[146:147], v[192:193]
	v_pk_fma_f32 v[32:33], v[32:33], v[148:149], v[194:195]
	v_pk_fma_f32 v[34:35], v[34:35], v[150:151], v[196:197]
	s_waitcnt lgkmcnt(2)
	v_pk_mul_f32 v[76:77], v[32:33], v[76:77]
	v_pk_mul_f32 v[202:203], v[32:33], v[202:203]
	v_pk_mul_f32 v[78:79], v[34:35], v[78:79]
	v_pk_mul_f32 v[204:205], v[34:35], v[204:205]
	v_pk_fma_f32 v[72:73], v[36:37], v[72:73], v[76:77]
	v_pk_fma_f32 v[198:199], v[36:37], v[198:199], v[202:203]
	v_pk_fma_f32 v[74:75], v[38:39], v[74:75], v[78:79]
	v_pk_fma_f32 v[200:201], v[38:39], v[200:201], v[204:205]
	v_pk_add_f32 v[72:73], v[72:73], v[74:75]
	v_pk_add_f32 v[198:199], v[198:199], v[200:201]
	v_add_f32_e32 v142, v72, v73
	v_add_f32_e32 v143, v198, v199
	ds_read_b128 v[156:159], v124 offset:20240
	v_add_f32_dpp v142, v142, v142 quad_perm:[1,0,3,2] row_mask:0xf bank_mask:0xf bound_ctrl:1
	v_add_f32_dpp v143, v143, v143 quad_perm:[1,0,3,2] row_mask:0xf bank_mask:0xf bound_ctrl:1
	ds_read_b128 v[152:155], v124 offset:20224
	v_add_f32_dpp v142, v142, v142 quad_perm:[2,3,0,1] row_mask:0xf bank_mask:0xf bound_ctrl:1
	v_add_f32_dpp v143, v143, v143 quad_perm:[2,3,0,1] row_mask:0xf bank_mask:0xf bound_ctrl:1
	ds_read_b128 v[182:185], v124 offset:20480
	v_add_f32_dpp v142, v142, v142 row_half_mirror row_mask:0xf bank_mask:0xf bound_ctrl:1
	v_add_f32_dpp v143, v143, v143 row_half_mirror row_mask:0xf bank_mask:0xf bound_ctrl:1
	ds_read_b128 v[186:189], v124 offset:20496
	ds_read_b32 v160, v135 offset:21248
	ds_read_b128 v[190:193], v124 offset:20736
	ds_read_b128 v[194:197], v124 offset:20752
	ds_read_b128 v[144:147], v124 offset:19968
	ds_read_b128 v[148:151], v124 offset:19984
	v_pk_mul_f32 v[68:69], v[68:69], v[142:143] op_sel_hi:[1,0]
	v_pk_mul_f32 v[70:71], v[70:71], v[142:143] op_sel_hi:[1,0]
	s_lshl_b64 vcc, vcc, 1
	v_pk_mul_f32 v[56:57], v[56:57], v[142:143] op_sel_hi:[1,0]
	v_pk_mul_f32 v[58:59], v[58:59], v[142:143] op_sel_hi:[1,0]
	v_pk_fma_f32 v[64:65], v[64:65], v[0:1], v[68:69] op_sel_hi:[1,0,1] neg_lo:[0,0,1] neg_hi:[0,0,1]
	v_pk_fma_f32 v[66:67], v[66:67], v[0:1], v[70:71] op_sel_hi:[1,0,1] neg_lo:[0,0,1] neg_hi:[0,0,1]
	v_cndmask_b32_e32 v133, v133, v143, vcc
	v_pk_fma_f32 v[60:61], v[60:61], v[0:1], v[56:57] op_sel_hi:[1,0,1] neg_lo:[0,0,1] neg_hi:[0,0,1]
	v_pk_fma_f32 v[62:63], v[62:63], v[0:1], v[58:59] op_sel_hi:[1,0,1] neg_lo:[0,0,1] neg_hi:[0,0,1]
	ds_read_b128 v[202:205], v124 offset:21008
	ds_read_b128 v[198:201], v124 offset:20992
	v_pk_fma_f32 v[36:37], v[36:37], v[48:49], v[64:65]
	v_pk_fma_f32 v[38:39], v[38:39], v[50:51], v[66:67]
	v_pk_fma_f32 v[32:33], v[32:33], v[40:41], v[60:61]
	v_pk_fma_f32 v[34:35], v[34:35], v[42:43], v[62:63]
	s_waitcnt lgkmcnt(2)
	v_pk_mul_f32 v[156:157], v[32:33], v[156:157]
	v_pk_mul_f32 v[52:53], v[32:33], v[52:53]
	v_pk_mul_f32 v[158:159], v[34:35], v[158:159]
	v_pk_mul_f32 v[54:55], v[34:35], v[54:55]
	v_pk_fma_f32 v[152:153], v[36:37], v[152:153], v[156:157]
	v_pk_fma_f32 v[44:45], v[36:37], v[44:45], v[52:53]
	v_pk_fma_f32 v[154:155], v[38:39], v[154:155], v[158:159]
	v_pk_fma_f32 v[46:47], v[38:39], v[46:47], v[54:55]
	v_pk_add_f32 v[152:153], v[152:153], v[154:155]
	v_pk_add_f32 v[44:45], v[44:45], v[46:47]
	v_add_f32_e32 v142, v152, v153
	v_add_f32_e32 v143, v44, v45
	ds_read_b128 v[76:79], v124 offset:21776
	v_add_f32_dpp v142, v142, v142 quad_perm:[1,0,3,2] row_mask:0xf bank_mask:0xf bound_ctrl:1
	v_add_f32_dpp v143, v143, v143 quad_perm:[1,0,3,2] row_mask:0xf bank_mask:0xf bound_ctrl:1
	ds_read_b128 v[72:75], v124 offset:21760
	v_add_f32_dpp v142, v142, v142 quad_perm:[2,3,0,1] row_mask:0xf bank_mask:0xf bound_ctrl:1
	v_add_f32_dpp v143, v143, v143 quad_perm:[2,3,0,1] row_mask:0xf bank_mask:0xf bound_ctrl:1
	ds_read_b128 v[68:71], v124 offset:22016
	v_add_f32_dpp v142, v142, v142 row_half_mirror row_mask:0xf bank_mask:0xf bound_ctrl:1
	v_add_f32_dpp v143, v143, v143 row_half_mirror row_mask:0xf bank_mask:0xf bound_ctrl:1
	ds_read_b128 v[56:59], v124 offset:22032
	ds_read_b32 v0, v135 offset:22784
	ds_read_b128 v[64:67], v124 offset:22272
	ds_read_b128 v[60:63], v124 offset:22288
	ds_read_b128 v[48:51], v124 offset:21504
	ds_read_b128 v[40:43], v124 offset:21520
	v_pk_mul_f32 v[182:183], v[182:183], v[142:143] op_sel_hi:[1,0]
	v_pk_mul_f32 v[184:185], v[184:185], v[142:143] op_sel_hi:[1,0]
	s_lshl_b64 vcc, vcc, 1
	v_pk_mul_f32 v[186:187], v[186:187], v[142:143] op_sel_hi:[1,0]
	v_pk_mul_f32 v[188:189], v[188:189], v[142:143] op_sel_hi:[1,0]
	v_pk_fma_f32 v[190:191], v[190:191], v[160:161], v[182:183] op_sel_hi:[1,0,1] neg_lo:[0,0,1] neg_hi:[0,0,1]
	v_pk_fma_f32 v[192:193], v[192:193], v[160:161], v[184:185] op_sel_hi:[1,0,1] neg_lo:[0,0,1] neg_hi:[0,0,1]
	v_cndmask_b32_e32 v133, v133, v143, vcc
	v_pk_fma_f32 v[194:195], v[194:195], v[160:161], v[186:187] op_sel_hi:[1,0,1] neg_lo:[0,0,1] neg_hi:[0,0,1]
	v_pk_fma_f32 v[196:197], v[196:197], v[160:161], v[188:189] op_sel_hi:[1,0,1] neg_lo:[0,0,1] neg_hi:[0,0,1]
	ds_read_b128 v[52:55], v124 offset:22544
	ds_read_b128 v[44:47], v124 offset:22528
	v_pk_fma_f32 v[36:37], v[36:37], v[144:145], v[190:191]
	v_pk_fma_f32 v[38:39], v[38:39], v[146:147], v[192:193]
	v_pk_fma_f32 v[32:33], v[32:33], v[148:149], v[194:195]
	v_pk_fma_f32 v[34:35], v[34:35], v[150:151], v[196:197]
	s_waitcnt lgkmcnt(2)
	v_pk_mul_f32 v[76:77], v[32:33], v[76:77]
	v_pk_mul_f32 v[202:203], v[32:33], v[202:203]
	v_pk_mul_f32 v[78:79], v[34:35], v[78:79]
	v_pk_mul_f32 v[204:205], v[34:35], v[204:205]
	v_pk_fma_f32 v[72:73], v[36:37], v[72:73], v[76:77]
	v_pk_fma_f32 v[198:199], v[36:37], v[198:199], v[202:203]
	v_pk_fma_f32 v[74:75], v[38:39], v[74:75], v[78:79]
	v_pk_fma_f32 v[200:201], v[38:39], v[200:201], v[204:205]
	v_pk_add_f32 v[72:73], v[72:73], v[74:75]
	v_pk_add_f32 v[198:199], v[198:199], v[200:201]
	v_add_f32_e32 v142, v72, v73
	v_add_f32_e32 v143, v198, v199
	ds_read_b128 v[156:159], v124 offset:23312
	v_add_f32_dpp v142, v142, v142 quad_perm:[1,0,3,2] row_mask:0xf bank_mask:0xf bound_ctrl:1
	v_add_f32_dpp v143, v143, v143 quad_perm:[1,0,3,2] row_mask:0xf bank_mask:0xf bound_ctrl:1
	ds_read_b128 v[152:155], v124 offset:23296
	v_add_f32_dpp v142, v142, v142 quad_perm:[2,3,0,1] row_mask:0xf bank_mask:0xf bound_ctrl:1
	v_add_f32_dpp v143, v143, v143 quad_perm:[2,3,0,1] row_mask:0xf bank_mask:0xf bound_ctrl:1
	ds_read_b128 v[182:185], v124 offset:23552
	v_add_f32_dpp v142, v142, v142 row_half_mirror row_mask:0xf bank_mask:0xf bound_ctrl:1
	v_add_f32_dpp v143, v143, v143 row_half_mirror row_mask:0xf bank_mask:0xf bound_ctrl:1
	ds_read_b128 v[186:189], v124 offset:23568
	ds_read_b32 v160, v135 offset:24320
	ds_read_b128 v[190:193], v124 offset:23808
	ds_read_b128 v[194:197], v124 offset:23824
	ds_read_b128 v[144:147], v124 offset:23040
	ds_read_b128 v[148:151], v124 offset:23056
	v_pk_mul_f32 v[68:69], v[68:69], v[142:143] op_sel_hi:[1,0]
	v_pk_mul_f32 v[70:71], v[70:71], v[142:143] op_sel_hi:[1,0]
	s_lshl_b64 vcc, vcc, 1
	v_pk_mul_f32 v[56:57], v[56:57], v[142:143] op_sel_hi:[1,0]
	v_pk_mul_f32 v[58:59], v[58:59], v[142:143] op_sel_hi:[1,0]
	v_pk_fma_f32 v[64:65], v[64:65], v[0:1], v[68:69] op_sel_hi:[1,0,1] neg_lo:[0,0,1] neg_hi:[0,0,1]
	v_pk_fma_f32 v[66:67], v[66:67], v[0:1], v[70:71] op_sel_hi:[1,0,1] neg_lo:[0,0,1] neg_hi:[0,0,1]
	v_cndmask_b32_e32 v133, v133, v143, vcc
	v_pk_fma_f32 v[60:61], v[60:61], v[0:1], v[56:57] op_sel_hi:[1,0,1] neg_lo:[0,0,1] neg_hi:[0,0,1]
	v_pk_fma_f32 v[62:63], v[62:63], v[0:1], v[58:59] op_sel_hi:[1,0,1] neg_lo:[0,0,1] neg_hi:[0,0,1]
	ds_read_b128 v[202:205], v124 offset:24080
	ds_read_b128 v[198:201], v124 offset:24064
	v_pk_fma_f32 v[36:37], v[36:37], v[48:49], v[64:65]
	v_pk_fma_f32 v[38:39], v[38:39], v[50:51], v[66:67]
	v_pk_fma_f32 v[32:33], v[32:33], v[40:41], v[60:61]
	v_pk_fma_f32 v[34:35], v[34:35], v[42:43], v[62:63]
	s_waitcnt lgkmcnt(2)
	v_pk_mul_f32 v[156:157], v[32:33], v[156:157]
	v_pk_mul_f32 v[52:53], v[32:33], v[52:53]
	v_pk_mul_f32 v[158:159], v[34:35], v[158:159]
	v_pk_mul_f32 v[54:55], v[34:35], v[54:55]
	v_pk_fma_f32 v[152:153], v[36:37], v[152:153], v[156:157]
	v_pk_fma_f32 v[44:45], v[36:37], v[44:45], v[52:53]
	v_pk_fma_f32 v[154:155], v[38:39], v[154:155], v[158:159]
	v_pk_fma_f32 v[46:47], v[38:39], v[46:47], v[54:55]
	v_pk_add_f32 v[152:153], v[152:153], v[154:155]
	v_pk_add_f32 v[44:45], v[44:45], v[46:47]
	v_add_f32_e32 v142, v152, v153
	v_add_f32_e32 v143, v44, v45
	ds_read_b128 v[76:79], v124 offset:24848
	v_add_f32_dpp v142, v142, v142 quad_perm:[1,0,3,2] row_mask:0xf bank_mask:0xf bound_ctrl:1
	v_add_f32_dpp v143, v143, v143 quad_perm:[1,0,3,2] row_mask:0xf bank_mask:0xf bound_ctrl:1
	ds_read_b128 v[72:75], v124 offset:24832
	v_add_f32_dpp v142, v142, v142 quad_perm:[2,3,0,1] row_mask:0xf bank_mask:0xf bound_ctrl:1
	v_add_f32_dpp v143, v143, v143 quad_perm:[2,3,0,1] row_mask:0xf bank_mask:0xf bound_ctrl:1
	ds_read_b128 v[68:71], v124 offset:25088
	v_add_f32_dpp v142, v142, v142 row_half_mirror row_mask:0xf bank_mask:0xf bound_ctrl:1
	v_add_f32_dpp v143, v143, v143 row_half_mirror row_mask:0xf bank_mask:0xf bound_ctrl:1
	ds_read_b128 v[56:59], v124 offset:25104
	ds_read_b32 v0, v135 offset:25856
	ds_read_b128 v[64:67], v124 offset:25344
	ds_read_b128 v[60:63], v124 offset:25360
	ds_read_b128 v[48:51], v124 offset:24576
	ds_read_b128 v[40:43], v124 offset:24592
	v_pk_mul_f32 v[182:183], v[182:183], v[142:143] op_sel_hi:[1,0]
	v_pk_mul_f32 v[184:185], v[184:185], v[142:143] op_sel_hi:[1,0]
	s_lshl_b64 vcc, vcc, 1
	v_pk_mul_f32 v[186:187], v[186:187], v[142:143] op_sel_hi:[1,0]
	v_pk_mul_f32 v[188:189], v[188:189], v[142:143] op_sel_hi:[1,0]
	v_pk_fma_f32 v[190:191], v[190:191], v[160:161], v[182:183] op_sel_hi:[1,0,1] neg_lo:[0,0,1] neg_hi:[0,0,1]
	v_pk_fma_f32 v[192:193], v[192:193], v[160:161], v[184:185] op_sel_hi:[1,0,1] neg_lo:[0,0,1] neg_hi:[0,0,1]
	v_cndmask_b32_e32 v133, v133, v143, vcc
	v_pk_fma_f32 v[194:195], v[194:195], v[160:161], v[186:187] op_sel_hi:[1,0,1] neg_lo:[0,0,1] neg_hi:[0,0,1]
	v_pk_fma_f32 v[196:197], v[196:197], v[160:161], v[188:189] op_sel_hi:[1,0,1] neg_lo:[0,0,1] neg_hi:[0,0,1]
	ds_read_b128 v[52:55], v124 offset:25616
	ds_read_b128 v[44:47], v124 offset:25600
	v_pk_fma_f32 v[36:37], v[36:37], v[144:145], v[190:191]
	v_pk_fma_f32 v[38:39], v[38:39], v[146:147], v[192:193]
	v_pk_fma_f32 v[32:33], v[32:33], v[148:149], v[194:195]
	v_pk_fma_f32 v[34:35], v[34:35], v[150:151], v[196:197]
	s_waitcnt lgkmcnt(2)
	v_pk_mul_f32 v[76:77], v[32:33], v[76:77]
	v_pk_mul_f32 v[202:203], v[32:33], v[202:203]
	v_pk_mul_f32 v[78:79], v[34:35], v[78:79]
	v_pk_mul_f32 v[204:205], v[34:35], v[204:205]
	v_pk_fma_f32 v[72:73], v[36:37], v[72:73], v[76:77]
	v_pk_fma_f32 v[198:199], v[36:37], v[198:199], v[202:203]
	v_pk_fma_f32 v[74:75], v[38:39], v[74:75], v[78:79]
	v_pk_fma_f32 v[200:201], v[38:39], v[200:201], v[204:205]
	v_pk_add_f32 v[72:73], v[72:73], v[74:75]
	v_pk_add_f32 v[198:199], v[198:199], v[200:201]
	v_add_f32_e32 v142, v72, v73
	v_add_f32_e32 v143, v198, v199
	ds_read_b128 v[156:159], v124 offset:26384
	v_add_f32_dpp v142, v142, v142 quad_perm:[1,0,3,2] row_mask:0xf bank_mask:0xf bound_ctrl:1
	v_add_f32_dpp v143, v143, v143 quad_perm:[1,0,3,2] row_mask:0xf bank_mask:0xf bound_ctrl:1
	ds_read_b128 v[152:155], v124 offset:26368
	v_add_f32_dpp v142, v142, v142 quad_perm:[2,3,0,1] row_mask:0xf bank_mask:0xf bound_ctrl:1
	v_add_f32_dpp v143, v143, v143 quad_perm:[2,3,0,1] row_mask:0xf bank_mask:0xf bound_ctrl:1
	ds_read_b128 v[182:185], v124 offset:26624
	v_add_f32_dpp v142, v142, v142 row_half_mirror row_mask:0xf bank_mask:0xf bound_ctrl:1
	v_add_f32_dpp v143, v143, v143 row_half_mirror row_mask:0xf bank_mask:0xf bound_ctrl:1
	ds_read_b128 v[186:189], v124 offset:26640
	ds_read_b32 v160, v135 offset:27392
	ds_read_b128 v[190:193], v124 offset:26880
	ds_read_b128 v[194:197], v124 offset:26896
	ds_read_b128 v[144:147], v124 offset:26112
	ds_read_b128 v[148:151], v124 offset:26128
	v_pk_mul_f32 v[68:69], v[68:69], v[142:143] op_sel_hi:[1,0]
	v_pk_mul_f32 v[70:71], v[70:71], v[142:143] op_sel_hi:[1,0]
	s_lshl_b64 vcc, vcc, 1
	v_pk_mul_f32 v[56:57], v[56:57], v[142:143] op_sel_hi:[1,0]
	v_pk_mul_f32 v[58:59], v[58:59], v[142:143] op_sel_hi:[1,0]
	v_pk_fma_f32 v[64:65], v[64:65], v[0:1], v[68:69] op_sel_hi:[1,0,1] neg_lo:[0,0,1] neg_hi:[0,0,1]
	v_pk_fma_f32 v[66:67], v[66:67], v[0:1], v[70:71] op_sel_hi:[1,0,1] neg_lo:[0,0,1] neg_hi:[0,0,1]
	v_cndmask_b32_e32 v133, v133, v143, vcc
	v_pk_fma_f32 v[60:61], v[60:61], v[0:1], v[56:57] op_sel_hi:[1,0,1] neg_lo:[0,0,1] neg_hi:[0,0,1]
	v_pk_fma_f32 v[62:63], v[62:63], v[0:1], v[58:59] op_sel_hi:[1,0,1] neg_lo:[0,0,1] neg_hi:[0,0,1]
	ds_read_b128 v[202:205], v124 offset:27152
	ds_read_b128 v[198:201], v124 offset:27136
	v_pk_fma_f32 v[36:37], v[36:37], v[48:49], v[64:65]
	v_pk_fma_f32 v[38:39], v[38:39], v[50:51], v[66:67]
	v_pk_fma_f32 v[32:33], v[32:33], v[40:41], v[60:61]
	v_pk_fma_f32 v[34:35], v[34:35], v[42:43], v[62:63]
	s_waitcnt lgkmcnt(2)
	v_pk_mul_f32 v[156:157], v[32:33], v[156:157]
	v_pk_mul_f32 v[52:53], v[32:33], v[52:53]
	v_pk_mul_f32 v[158:159], v[34:35], v[158:159]
	v_pk_mul_f32 v[54:55], v[34:35], v[54:55]
	v_pk_fma_f32 v[152:153], v[36:37], v[152:153], v[156:157]
	v_pk_fma_f32 v[44:45], v[36:37], v[44:45], v[52:53]
	v_pk_fma_f32 v[154:155], v[38:39], v[154:155], v[158:159]
	v_pk_fma_f32 v[46:47], v[38:39], v[46:47], v[54:55]
	v_pk_add_f32 v[152:153], v[152:153], v[154:155]
	v_pk_add_f32 v[44:45], v[44:45], v[46:47]
	v_add_f32_e32 v142, v152, v153
	v_add_f32_e32 v143, v44, v45
	ds_read_b128 v[76:79], v124 offset:27920
	v_add_f32_dpp v142, v142, v142 quad_perm:[1,0,3,2] row_mask:0xf bank_mask:0xf bound_ctrl:1
	v_add_f32_dpp v143, v143, v143 quad_perm:[1,0,3,2] row_mask:0xf bank_mask:0xf bound_ctrl:1
	ds_read_b128 v[72:75], v124 offset:27904
	v_add_f32_dpp v142, v142, v142 quad_perm:[2,3,0,1] row_mask:0xf bank_mask:0xf bound_ctrl:1
	v_add_f32_dpp v143, v143, v143 quad_perm:[2,3,0,1] row_mask:0xf bank_mask:0xf bound_ctrl:1
	ds_read_b128 v[68:71], v124 offset:28160
	v_add_f32_dpp v142, v142, v142 row_half_mirror row_mask:0xf bank_mask:0xf bound_ctrl:1
	v_add_f32_dpp v143, v143, v143 row_half_mirror row_mask:0xf bank_mask:0xf bound_ctrl:1
	ds_read_b128 v[56:59], v124 offset:28176
	ds_read_b32 v0, v135 offset:28928
	ds_read_b128 v[64:67], v124 offset:28416
	ds_read_b128 v[60:63], v124 offset:28432
	ds_read_b128 v[48:51], v124 offset:27648
	ds_read_b128 v[40:43], v124 offset:27664
	v_pk_mul_f32 v[182:183], v[182:183], v[142:143] op_sel_hi:[1,0]
	v_pk_mul_f32 v[184:185], v[184:185], v[142:143] op_sel_hi:[1,0]
	s_mov_b32 vcc_lo, 0x1010101
	v_pk_mul_f32 v[186:187], v[186:187], v[142:143] op_sel_hi:[1,0]
	v_pk_mul_f32 v[188:189], v[188:189], v[142:143] op_sel_hi:[1,0]
	s_mov_b32 vcc_hi, 0x1010101
	v_pk_fma_f32 v[190:191], v[190:191], v[160:161], v[182:183] op_sel_hi:[1,0,1] neg_lo:[0,0,1] neg_hi:[0,0,1]
	v_pk_fma_f32 v[192:193], v[192:193], v[160:161], v[184:185] op_sel_hi:[1,0,1] neg_lo:[0,0,1] neg_hi:[0,0,1]
	v_cndmask_b32_e32 v132, v132, v143, vcc
	v_pk_fma_f32 v[194:195], v[194:195], v[160:161], v[186:187] op_sel_hi:[1,0,1] neg_lo:[0,0,1] neg_hi:[0,0,1]
	v_pk_fma_f32 v[196:197], v[196:197], v[160:161], v[188:189] op_sel_hi:[1,0,1] neg_lo:[0,0,1] neg_hi:[0,0,1]
	ds_read_b128 v[52:55], v124 offset:28688
	ds_read_b128 v[44:47], v124 offset:28672
	v_pk_fma_f32 v[36:37], v[36:37], v[144:145], v[190:191]
	v_pk_fma_f32 v[38:39], v[38:39], v[146:147], v[192:193]
	v_pk_fma_f32 v[32:33], v[32:33], v[148:149], v[194:195]
	v_pk_fma_f32 v[34:35], v[34:35], v[150:151], v[196:197]
	s_waitcnt lgkmcnt(2)
	v_pk_mul_f32 v[76:77], v[32:33], v[76:77]
	v_pk_mul_f32 v[202:203], v[32:33], v[202:203]
	v_pk_mul_f32 v[78:79], v[34:35], v[78:79]
	v_pk_mul_f32 v[204:205], v[34:35], v[204:205]
	v_pk_fma_f32 v[72:73], v[36:37], v[72:73], v[76:77]
	v_pk_fma_f32 v[198:199], v[36:37], v[198:199], v[202:203]
	v_pk_fma_f32 v[74:75], v[38:39], v[74:75], v[78:79]
	v_pk_fma_f32 v[200:201], v[38:39], v[200:201], v[204:205]
	v_pk_add_f32 v[72:73], v[72:73], v[74:75]
	v_pk_add_f32 v[198:199], v[198:199], v[200:201]
	v_add_f32_e32 v142, v72, v73
	v_add_f32_e32 v143, v198, v199
	ds_read_b128 v[156:159], v124 offset:29456
	v_add_f32_dpp v142, v142, v142 quad_perm:[1,0,3,2] row_mask:0xf bank_mask:0xf bound_ctrl:1
	v_add_f32_dpp v143, v143, v143 quad_perm:[1,0,3,2] row_mask:0xf bank_mask:0xf bound_ctrl:1
	ds_read_b128 v[152:155], v124 offset:29440
	v_add_f32_dpp v142, v142, v142 quad_perm:[2,3,0,1] row_mask:0xf bank_mask:0xf bound_ctrl:1
	v_add_f32_dpp v143, v143, v143 quad_perm:[2,3,0,1] row_mask:0xf bank_mask:0xf bound_ctrl:1
	ds_read_b128 v[182:185], v124 offset:29696
	v_add_f32_dpp v142, v142, v142 row_half_mirror row_mask:0xf bank_mask:0xf bound_ctrl:1
	v_add_f32_dpp v143, v143, v143 row_half_mirror row_mask:0xf bank_mask:0xf bound_ctrl:1
	ds_read_b128 v[186:189], v124 offset:29712
	ds_read_b32 v160, v135 offset:30464
	ds_read_b128 v[190:193], v124 offset:29952
	ds_read_b128 v[194:197], v124 offset:29968
	ds_read_b128 v[144:147], v124 offset:29184
	ds_read_b128 v[148:151], v124 offset:29200
	v_pk_mul_f32 v[68:69], v[68:69], v[142:143] op_sel_hi:[1,0]
	v_pk_mul_f32 v[70:71], v[70:71], v[142:143] op_sel_hi:[1,0]
	s_lshl_b64 vcc, vcc, 1
	v_pk_mul_f32 v[56:57], v[56:57], v[142:143] op_sel_hi:[1,0]
	v_pk_mul_f32 v[58:59], v[58:59], v[142:143] op_sel_hi:[1,0]
	v_pk_fma_f32 v[64:65], v[64:65], v[0:1], v[68:69] op_sel_hi:[1,0,1] neg_lo:[0,0,1] neg_hi:[0,0,1]
	v_pk_fma_f32 v[66:67], v[66:67], v[0:1], v[70:71] op_sel_hi:[1,0,1] neg_lo:[0,0,1] neg_hi:[0,0,1]
	v_cndmask_b32_e32 v132, v132, v143, vcc
	v_pk_fma_f32 v[60:61], v[60:61], v[0:1], v[56:57] op_sel_hi:[1,0,1] neg_lo:[0,0,1] neg_hi:[0,0,1]
	v_pk_fma_f32 v[62:63], v[62:63], v[0:1], v[58:59] op_sel_hi:[1,0,1] neg_lo:[0,0,1] neg_hi:[0,0,1]
	ds_read_b128 v[202:205], v124 offset:30224
	ds_read_b128 v[198:201], v124 offset:30208
	v_pk_fma_f32 v[36:37], v[36:37], v[48:49], v[64:65]
	v_pk_fma_f32 v[38:39], v[38:39], v[50:51], v[66:67]
	v_pk_fma_f32 v[32:33], v[32:33], v[40:41], v[60:61]
	v_pk_fma_f32 v[34:35], v[34:35], v[42:43], v[62:63]
	s_waitcnt lgkmcnt(2)
	v_pk_mul_f32 v[156:157], v[32:33], v[156:157]
	v_pk_mul_f32 v[52:53], v[32:33], v[52:53]
	v_pk_mul_f32 v[158:159], v[34:35], v[158:159]
	v_pk_mul_f32 v[54:55], v[34:35], v[54:55]
	v_pk_fma_f32 v[152:153], v[36:37], v[152:153], v[156:157]
	v_pk_fma_f32 v[44:45], v[36:37], v[44:45], v[52:53]
	v_pk_fma_f32 v[154:155], v[38:39], v[154:155], v[158:159]
	v_pk_fma_f32 v[46:47], v[38:39], v[46:47], v[54:55]
	v_pk_add_f32 v[152:153], v[152:153], v[154:155]
	v_pk_add_f32 v[44:45], v[44:45], v[46:47]
	v_add_f32_e32 v142, v152, v153
	v_add_f32_e32 v143, v44, v45
	ds_read_b128 v[76:79], v124 offset:30992
	v_add_f32_dpp v142, v142, v142 quad_perm:[1,0,3,2] row_mask:0xf bank_mask:0xf bound_ctrl:1
	v_add_f32_dpp v143, v143, v143 quad_perm:[1,0,3,2] row_mask:0xf bank_mask:0xf bound_ctrl:1
	ds_read_b128 v[72:75], v124 offset:30976
	v_add_f32_dpp v142, v142, v142 quad_perm:[2,3,0,1] row_mask:0xf bank_mask:0xf bound_ctrl:1
	v_add_f32_dpp v143, v143, v143 quad_perm:[2,3,0,1] row_mask:0xf bank_mask:0xf bound_ctrl:1
	ds_read_b128 v[68:71], v124 offset:31232
	v_add_f32_dpp v142, v142, v142 row_half_mirror row_mask:0xf bank_mask:0xf bound_ctrl:1
	v_add_f32_dpp v143, v143, v143 row_half_mirror row_mask:0xf bank_mask:0xf bound_ctrl:1
	ds_read_b128 v[56:59], v124 offset:31248
	ds_read_b32 v0, v135 offset:32000
	ds_read_b128 v[64:67], v124 offset:31488
	ds_read_b128 v[60:63], v124 offset:31504
	ds_read_b128 v[48:51], v124 offset:30720
	ds_read_b128 v[40:43], v124 offset:30736
	v_pk_mul_f32 v[182:183], v[182:183], v[142:143] op_sel_hi:[1,0]
	v_pk_mul_f32 v[184:185], v[184:185], v[142:143] op_sel_hi:[1,0]
	s_lshl_b64 vcc, vcc, 1
	v_pk_mul_f32 v[186:187], v[186:187], v[142:143] op_sel_hi:[1,0]
	v_pk_mul_f32 v[188:189], v[188:189], v[142:143] op_sel_hi:[1,0]
	v_pk_fma_f32 v[190:191], v[190:191], v[160:161], v[182:183] op_sel_hi:[1,0,1] neg_lo:[0,0,1] neg_hi:[0,0,1]
	v_pk_fma_f32 v[192:193], v[192:193], v[160:161], v[184:185] op_sel_hi:[1,0,1] neg_lo:[0,0,1] neg_hi:[0,0,1]
	v_cndmask_b32_e32 v132, v132, v143, vcc
	v_pk_fma_f32 v[194:195], v[194:195], v[160:161], v[186:187] op_sel_hi:[1,0,1] neg_lo:[0,0,1] neg_hi:[0,0,1]
	v_pk_fma_f32 v[196:197], v[196:197], v[160:161], v[188:189] op_sel_hi:[1,0,1] neg_lo:[0,0,1] neg_hi:[0,0,1]
	ds_read_b128 v[52:55], v124 offset:31760
	ds_read_b128 v[44:47], v124 offset:31744
	v_pk_fma_f32 v[36:37], v[36:37], v[144:145], v[190:191]
	v_pk_fma_f32 v[38:39], v[38:39], v[146:147], v[192:193]
	v_pk_fma_f32 v[32:33], v[32:33], v[148:149], v[194:195]
	v_pk_fma_f32 v[34:35], v[34:35], v[150:151], v[196:197]
	s_waitcnt lgkmcnt(2)
	v_pk_mul_f32 v[76:77], v[32:33], v[76:77]
	v_pk_mul_f32 v[202:203], v[32:33], v[202:203]
	v_pk_mul_f32 v[78:79], v[34:35], v[78:79]
	v_pk_mul_f32 v[204:205], v[34:35], v[204:205]
	v_pk_fma_f32 v[72:73], v[36:37], v[72:73], v[76:77]
	v_pk_fma_f32 v[198:199], v[36:37], v[198:199], v[202:203]
	v_pk_fma_f32 v[74:75], v[38:39], v[74:75], v[78:79]
	v_pk_fma_f32 v[200:201], v[38:39], v[200:201], v[204:205]
	v_pk_add_f32 v[72:73], v[72:73], v[74:75]
	v_pk_add_f32 v[198:199], v[198:199], v[200:201]
	v_add_f32_e32 v142, v72, v73
	v_add_f32_e32 v143, v198, v199
	ds_read_b128 v[156:159], v124 offset:32528
	v_add_f32_dpp v142, v142, v142 quad_perm:[1,0,3,2] row_mask:0xf bank_mask:0xf bound_ctrl:1
	v_add_f32_dpp v143, v143, v143 quad_perm:[1,0,3,2] row_mask:0xf bank_mask:0xf bound_ctrl:1
	ds_read_b128 v[152:155], v124 offset:32512
	v_add_f32_dpp v142, v142, v142 quad_perm:[2,3,0,1] row_mask:0xf bank_mask:0xf bound_ctrl:1
	v_add_f32_dpp v143, v143, v143 quad_perm:[2,3,0,1] row_mask:0xf bank_mask:0xf bound_ctrl:1
	ds_read_b128 v[182:185], v124 offset:32768
	v_add_f32_dpp v142, v142, v142 row_half_mirror row_mask:0xf bank_mask:0xf bound_ctrl:1
	v_add_f32_dpp v143, v143, v143 row_half_mirror row_mask:0xf bank_mask:0xf bound_ctrl:1
	ds_read_b128 v[186:189], v124 offset:32784
	ds_read_b32 v160, v135 offset:33536
	ds_read_b128 v[190:193], v124 offset:33024
	ds_read_b128 v[194:197], v124 offset:33040
	ds_read_b128 v[144:147], v124 offset:32256
	ds_read_b128 v[148:151], v124 offset:32272
	v_pk_mul_f32 v[68:69], v[68:69], v[142:143] op_sel_hi:[1,0]
	v_pk_mul_f32 v[70:71], v[70:71], v[142:143] op_sel_hi:[1,0]
	s_lshl_b64 vcc, vcc, 1
	v_pk_mul_f32 v[56:57], v[56:57], v[142:143] op_sel_hi:[1,0]
	v_pk_mul_f32 v[58:59], v[58:59], v[142:143] op_sel_hi:[1,0]
	v_pk_fma_f32 v[64:65], v[64:65], v[0:1], v[68:69] op_sel_hi:[1,0,1] neg_lo:[0,0,1] neg_hi:[0,0,1]
	v_pk_fma_f32 v[66:67], v[66:67], v[0:1], v[70:71] op_sel_hi:[1,0,1] neg_lo:[0,0,1] neg_hi:[0,0,1]
	v_cndmask_b32_e32 v132, v132, v143, vcc
	v_pk_fma_f32 v[60:61], v[60:61], v[0:1], v[56:57] op_sel_hi:[1,0,1] neg_lo:[0,0,1] neg_hi:[0,0,1]
	v_pk_fma_f32 v[62:63], v[62:63], v[0:1], v[58:59] op_sel_hi:[1,0,1] neg_lo:[0,0,1] neg_hi:[0,0,1]
	ds_read_b128 v[202:205], v124 offset:33296
	ds_read_b128 v[198:201], v124 offset:33280
	v_pk_fma_f32 v[36:37], v[36:37], v[48:49], v[64:65]
	v_pk_fma_f32 v[38:39], v[38:39], v[50:51], v[66:67]
	v_pk_fma_f32 v[32:33], v[32:33], v[40:41], v[60:61]
	v_pk_fma_f32 v[34:35], v[34:35], v[42:43], v[62:63]
	s_waitcnt lgkmcnt(2)
	v_pk_mul_f32 v[156:157], v[32:33], v[156:157]
	v_pk_mul_f32 v[52:53], v[32:33], v[52:53]
	v_pk_mul_f32 v[158:159], v[34:35], v[158:159]
	v_pk_mul_f32 v[54:55], v[34:35], v[54:55]
	v_pk_fma_f32 v[152:153], v[36:37], v[152:153], v[156:157]
	v_pk_fma_f32 v[44:45], v[36:37], v[44:45], v[52:53]
	v_pk_fma_f32 v[154:155], v[38:39], v[154:155], v[158:159]
	v_pk_fma_f32 v[46:47], v[38:39], v[46:47], v[54:55]
	v_pk_add_f32 v[152:153], v[152:153], v[154:155]
	v_pk_add_f32 v[44:45], v[44:45], v[46:47]
	v_add_f32_e32 v142, v152, v153
	v_add_f32_e32 v143, v44, v45
	ds_read_b128 v[76:79], v124 offset:34064
	v_add_f32_dpp v142, v142, v142 quad_perm:[1,0,3,2] row_mask:0xf bank_mask:0xf bound_ctrl:1
	v_add_f32_dpp v143, v143, v143 quad_perm:[1,0,3,2] row_mask:0xf bank_mask:0xf bound_ctrl:1
	ds_read_b128 v[72:75], v124 offset:34048
	v_add_f32_dpp v142, v142, v142 quad_perm:[2,3,0,1] row_mask:0xf bank_mask:0xf bound_ctrl:1
	v_add_f32_dpp v143, v143, v143 quad_perm:[2,3,0,1] row_mask:0xf bank_mask:0xf bound_ctrl:1
	ds_read_b128 v[68:71], v124 offset:34304
	v_add_f32_dpp v142, v142, v142 row_half_mirror row_mask:0xf bank_mask:0xf bound_ctrl:1
	v_add_f32_dpp v143, v143, v143 row_half_mirror row_mask:0xf bank_mask:0xf bound_ctrl:1
	ds_read_b128 v[56:59], v124 offset:34320
	ds_read_b32 v0, v135 offset:35072
	ds_read_b128 v[64:67], v124 offset:34560
	ds_read_b128 v[60:63], v124 offset:34576
	ds_read_b128 v[48:51], v124 offset:33792
	ds_read_b128 v[40:43], v124 offset:33808
	v_pk_mul_f32 v[182:183], v[182:183], v[142:143] op_sel_hi:[1,0]
	v_pk_mul_f32 v[184:185], v[184:185], v[142:143] op_sel_hi:[1,0]
	s_lshl_b64 vcc, vcc, 1
	v_pk_mul_f32 v[186:187], v[186:187], v[142:143] op_sel_hi:[1,0]
	v_pk_mul_f32 v[188:189], v[188:189], v[142:143] op_sel_hi:[1,0]
	v_pk_fma_f32 v[190:191], v[190:191], v[160:161], v[182:183] op_sel_hi:[1,0,1] neg_lo:[0,0,1] neg_hi:[0,0,1]
	v_pk_fma_f32 v[192:193], v[192:193], v[160:161], v[184:185] op_sel_hi:[1,0,1] neg_lo:[0,0,1] neg_hi:[0,0,1]
	v_cndmask_b32_e32 v132, v132, v143, vcc
	v_pk_fma_f32 v[194:195], v[194:195], v[160:161], v[186:187] op_sel_hi:[1,0,1] neg_lo:[0,0,1] neg_hi:[0,0,1]
	v_pk_fma_f32 v[196:197], v[196:197], v[160:161], v[188:189] op_sel_hi:[1,0,1] neg_lo:[0,0,1] neg_hi:[0,0,1]
	ds_read_b128 v[52:55], v124 offset:34832
	ds_read_b128 v[44:47], v124 offset:34816
	v_pk_fma_f32 v[36:37], v[36:37], v[144:145], v[190:191]
	v_pk_fma_f32 v[38:39], v[38:39], v[146:147], v[192:193]
	v_pk_fma_f32 v[32:33], v[32:33], v[148:149], v[194:195]
	v_pk_fma_f32 v[34:35], v[34:35], v[150:151], v[196:197]
	s_waitcnt lgkmcnt(2)
	v_pk_mul_f32 v[76:77], v[32:33], v[76:77]
	v_pk_mul_f32 v[202:203], v[32:33], v[202:203]
	v_pk_mul_f32 v[78:79], v[34:35], v[78:79]
	v_pk_mul_f32 v[204:205], v[34:35], v[204:205]
	v_pk_fma_f32 v[72:73], v[36:37], v[72:73], v[76:77]
	v_pk_fma_f32 v[198:199], v[36:37], v[198:199], v[202:203]
	v_pk_fma_f32 v[74:75], v[38:39], v[74:75], v[78:79]
	v_pk_fma_f32 v[200:201], v[38:39], v[200:201], v[204:205]
	v_pk_add_f32 v[72:73], v[72:73], v[74:75]
	v_pk_add_f32 v[198:199], v[198:199], v[200:201]
	v_add_f32_e32 v142, v72, v73
	v_add_f32_e32 v143, v198, v199
	ds_read_b128 v[156:159], v124 offset:35600
	v_add_f32_dpp v142, v142, v142 quad_perm:[1,0,3,2] row_mask:0xf bank_mask:0xf bound_ctrl:1
	v_add_f32_dpp v143, v143, v143 quad_perm:[1,0,3,2] row_mask:0xf bank_mask:0xf bound_ctrl:1
	ds_read_b128 v[152:155], v124 offset:35584
	v_add_f32_dpp v142, v142, v142 quad_perm:[2,3,0,1] row_mask:0xf bank_mask:0xf bound_ctrl:1
	v_add_f32_dpp v143, v143, v143 quad_perm:[2,3,0,1] row_mask:0xf bank_mask:0xf bound_ctrl:1
	ds_read_b128 v[182:185], v124 offset:35840
	v_add_f32_dpp v142, v142, v142 row_half_mirror row_mask:0xf bank_mask:0xf bound_ctrl:1
	v_add_f32_dpp v143, v143, v143 row_half_mirror row_mask:0xf bank_mask:0xf bound_ctrl:1
	ds_read_b128 v[186:189], v124 offset:35856
	ds_read_b32 v160, v135 offset:36608
	ds_read_b128 v[190:193], v124 offset:36096
	ds_read_b128 v[194:197], v124 offset:36112
	ds_read_b128 v[144:147], v124 offset:35328
	ds_read_b128 v[148:151], v124 offset:35344
	v_pk_mul_f32 v[68:69], v[68:69], v[142:143] op_sel_hi:[1,0]
	v_pk_mul_f32 v[70:71], v[70:71], v[142:143] op_sel_hi:[1,0]
	s_lshl_b64 vcc, vcc, 1
	v_pk_mul_f32 v[56:57], v[56:57], v[142:143] op_sel_hi:[1,0]
	v_pk_mul_f32 v[58:59], v[58:59], v[142:143] op_sel_hi:[1,0]
	v_pk_fma_f32 v[64:65], v[64:65], v[0:1], v[68:69] op_sel_hi:[1,0,1] neg_lo:[0,0,1] neg_hi:[0,0,1]
	v_pk_fma_f32 v[66:67], v[66:67], v[0:1], v[70:71] op_sel_hi:[1,0,1] neg_lo:[0,0,1] neg_hi:[0,0,1]
	v_cndmask_b32_e32 v132, v132, v143, vcc
	v_pk_fma_f32 v[60:61], v[60:61], v[0:1], v[56:57] op_sel_hi:[1,0,1] neg_lo:[0,0,1] neg_hi:[0,0,1]
	v_pk_fma_f32 v[62:63], v[62:63], v[0:1], v[58:59] op_sel_hi:[1,0,1] neg_lo:[0,0,1] neg_hi:[0,0,1]
	ds_read_b128 v[202:205], v124 offset:36368
	ds_read_b128 v[198:201], v124 offset:36352
	v_pk_fma_f32 v[36:37], v[36:37], v[48:49], v[64:65]
	v_pk_fma_f32 v[38:39], v[38:39], v[50:51], v[66:67]
	v_pk_fma_f32 v[32:33], v[32:33], v[40:41], v[60:61]
	v_pk_fma_f32 v[34:35], v[34:35], v[42:43], v[62:63]
	s_waitcnt lgkmcnt(2)
	v_pk_mul_f32 v[156:157], v[32:33], v[156:157]
	v_pk_mul_f32 v[52:53], v[32:33], v[52:53]
	v_pk_mul_f32 v[158:159], v[34:35], v[158:159]
	v_pk_mul_f32 v[54:55], v[34:35], v[54:55]
	v_pk_fma_f32 v[152:153], v[36:37], v[152:153], v[156:157]
	v_pk_fma_f32 v[44:45], v[36:37], v[44:45], v[52:53]
	v_pk_fma_f32 v[154:155], v[38:39], v[154:155], v[158:159]
	v_pk_fma_f32 v[46:47], v[38:39], v[46:47], v[54:55]
	v_pk_add_f32 v[152:153], v[152:153], v[154:155]
	v_pk_add_f32 v[44:45], v[44:45], v[46:47]
	v_add_f32_e32 v142, v152, v153
	v_add_f32_e32 v143, v44, v45
	ds_read_b128 v[76:79], v124 offset:37136
	v_add_f32_dpp v142, v142, v142 quad_perm:[1,0,3,2] row_mask:0xf bank_mask:0xf bound_ctrl:1
	v_add_f32_dpp v143, v143, v143 quad_perm:[1,0,3,2] row_mask:0xf bank_mask:0xf bound_ctrl:1
	ds_read_b128 v[72:75], v124 offset:37120
	v_add_f32_dpp v142, v142, v142 quad_perm:[2,3,0,1] row_mask:0xf bank_mask:0xf bound_ctrl:1
	v_add_f32_dpp v143, v143, v143 quad_perm:[2,3,0,1] row_mask:0xf bank_mask:0xf bound_ctrl:1
	ds_read_b128 v[68:71], v124 offset:37376
	v_add_f32_dpp v142, v142, v142 row_half_mirror row_mask:0xf bank_mask:0xf bound_ctrl:1
	v_add_f32_dpp v143, v143, v143 row_half_mirror row_mask:0xf bank_mask:0xf bound_ctrl:1
	ds_read_b128 v[56:59], v124 offset:37392
	ds_read_b32 v0, v135 offset:38144
	ds_read_b128 v[64:67], v124 offset:37632
	ds_read_b128 v[60:63], v124 offset:37648
	ds_read_b128 v[48:51], v124 offset:36864
	ds_read_b128 v[40:43], v124 offset:36880
	v_pk_mul_f32 v[182:183], v[182:183], v[142:143] op_sel_hi:[1,0]
	v_pk_mul_f32 v[184:185], v[184:185], v[142:143] op_sel_hi:[1,0]
	s_lshl_b64 vcc, vcc, 1
	v_pk_mul_f32 v[186:187], v[186:187], v[142:143] op_sel_hi:[1,0]
	v_pk_mul_f32 v[188:189], v[188:189], v[142:143] op_sel_hi:[1,0]
	v_pk_fma_f32 v[190:191], v[190:191], v[160:161], v[182:183] op_sel_hi:[1,0,1] neg_lo:[0,0,1] neg_hi:[0,0,1]
	v_pk_fma_f32 v[192:193], v[192:193], v[160:161], v[184:185] op_sel_hi:[1,0,1] neg_lo:[0,0,1] neg_hi:[0,0,1]
	v_cndmask_b32_e32 v132, v132, v143, vcc
	v_pk_fma_f32 v[194:195], v[194:195], v[160:161], v[186:187] op_sel_hi:[1,0,1] neg_lo:[0,0,1] neg_hi:[0,0,1]
	v_pk_fma_f32 v[196:197], v[196:197], v[160:161], v[188:189] op_sel_hi:[1,0,1] neg_lo:[0,0,1] neg_hi:[0,0,1]
	ds_read_b128 v[52:55], v124 offset:37904
	ds_read_b128 v[44:47], v124 offset:37888
	v_pk_fma_f32 v[36:37], v[36:37], v[144:145], v[190:191]
	v_pk_fma_f32 v[38:39], v[38:39], v[146:147], v[192:193]
	v_pk_fma_f32 v[32:33], v[32:33], v[148:149], v[194:195]
	v_pk_fma_f32 v[34:35], v[34:35], v[150:151], v[196:197]
	s_waitcnt lgkmcnt(2)
	v_pk_mul_f32 v[76:77], v[32:33], v[76:77]
	v_pk_mul_f32 v[202:203], v[32:33], v[202:203]
	v_pk_mul_f32 v[78:79], v[34:35], v[78:79]
	v_pk_mul_f32 v[204:205], v[34:35], v[204:205]
	v_pk_fma_f32 v[72:73], v[36:37], v[72:73], v[76:77]
	v_pk_fma_f32 v[198:199], v[36:37], v[198:199], v[202:203]
	v_pk_fma_f32 v[74:75], v[38:39], v[74:75], v[78:79]
	v_pk_fma_f32 v[200:201], v[38:39], v[200:201], v[204:205]
	v_pk_add_f32 v[72:73], v[72:73], v[74:75]
	v_pk_add_f32 v[198:199], v[198:199], v[200:201]
	v_add_f32_e32 v142, v72, v73
	v_add_f32_e32 v143, v198, v199
	ds_read_b128 v[156:159], v124 offset:38672
	v_add_f32_dpp v142, v142, v142 quad_perm:[1,0,3,2] row_mask:0xf bank_mask:0xf bound_ctrl:1
	v_add_f32_dpp v143, v143, v143 quad_perm:[1,0,3,2] row_mask:0xf bank_mask:0xf bound_ctrl:1
	ds_read_b128 v[152:155], v124 offset:38656
	v_add_f32_dpp v142, v142, v142 quad_perm:[2,3,0,1] row_mask:0xf bank_mask:0xf bound_ctrl:1
	v_add_f32_dpp v143, v143, v143 quad_perm:[2,3,0,1] row_mask:0xf bank_mask:0xf bound_ctrl:1
	ds_read_b128 v[182:185], v124 offset:38912
	v_add_f32_dpp v142, v142, v142 row_half_mirror row_mask:0xf bank_mask:0xf bound_ctrl:1
	v_add_f32_dpp v143, v143, v143 row_half_mirror row_mask:0xf bank_mask:0xf bound_ctrl:1
	ds_read_b128 v[186:189], v124 offset:38928
	ds_read_b32 v160, v135 offset:39680
	ds_read_b128 v[190:193], v124 offset:39168
	ds_read_b128 v[194:197], v124 offset:39184
	ds_read_b128 v[144:147], v124 offset:38400
	ds_read_b128 v[148:151], v124 offset:38416
	v_pk_mul_f32 v[68:69], v[68:69], v[142:143] op_sel_hi:[1,0]
	v_pk_mul_f32 v[70:71], v[70:71], v[142:143] op_sel_hi:[1,0]
	s_lshl_b64 vcc, vcc, 1
	v_pk_mul_f32 v[56:57], v[56:57], v[142:143] op_sel_hi:[1,0]
	v_pk_mul_f32 v[58:59], v[58:59], v[142:143] op_sel_hi:[1,0]
	v_pk_fma_f32 v[64:65], v[64:65], v[0:1], v[68:69] op_sel_hi:[1,0,1] neg_lo:[0,0,1] neg_hi:[0,0,1]
	v_pk_fma_f32 v[66:67], v[66:67], v[0:1], v[70:71] op_sel_hi:[1,0,1] neg_lo:[0,0,1] neg_hi:[0,0,1]
	v_cndmask_b32_e32 v132, v132, v143, vcc
	v_pk_fma_f32 v[60:61], v[60:61], v[0:1], v[56:57] op_sel_hi:[1,0,1] neg_lo:[0,0,1] neg_hi:[0,0,1]
	v_pk_fma_f32 v[62:63], v[62:63], v[0:1], v[58:59] op_sel_hi:[1,0,1] neg_lo:[0,0,1] neg_hi:[0,0,1]
	ds_read_b128 v[202:205], v124 offset:39440
	ds_read_b128 v[198:201], v124 offset:39424
	v_pk_fma_f32 v[36:37], v[36:37], v[48:49], v[64:65]
	v_pk_fma_f32 v[38:39], v[38:39], v[50:51], v[66:67]
	v_pk_fma_f32 v[32:33], v[32:33], v[40:41], v[60:61]
	v_pk_fma_f32 v[34:35], v[34:35], v[42:43], v[62:63]
	s_waitcnt lgkmcnt(2)
	v_pk_mul_f32 v[156:157], v[32:33], v[156:157]
	v_pk_mul_f32 v[52:53], v[32:33], v[52:53]
	v_pk_mul_f32 v[158:159], v[34:35], v[158:159]
	v_pk_mul_f32 v[54:55], v[34:35], v[54:55]
	v_pk_fma_f32 v[152:153], v[36:37], v[152:153], v[156:157]
	v_pk_fma_f32 v[44:45], v[36:37], v[44:45], v[52:53]
	v_pk_fma_f32 v[154:155], v[38:39], v[154:155], v[158:159]
	v_pk_fma_f32 v[46:47], v[38:39], v[46:47], v[54:55]
	v_pk_add_f32 v[152:153], v[152:153], v[154:155]
	v_pk_add_f32 v[44:45], v[44:45], v[46:47]
	v_add_f32_e32 v142, v152, v153
	v_add_f32_e32 v143, v44, v45
	ds_read_b128 v[76:79], v124 offset:40208
	v_add_f32_dpp v142, v142, v142 quad_perm:[1,0,3,2] row_mask:0xf bank_mask:0xf bound_ctrl:1
	v_add_f32_dpp v143, v143, v143 quad_perm:[1,0,3,2] row_mask:0xf bank_mask:0xf bound_ctrl:1
	ds_read_b128 v[72:75], v124 offset:40192
	v_add_f32_dpp v142, v142, v142 quad_perm:[2,3,0,1] row_mask:0xf bank_mask:0xf bound_ctrl:1
	v_add_f32_dpp v143, v143, v143 quad_perm:[2,3,0,1] row_mask:0xf bank_mask:0xf bound_ctrl:1
	ds_read_b128 v[68:71], v124 offset:40448
	v_add_f32_dpp v142, v142, v142 row_half_mirror row_mask:0xf bank_mask:0xf bound_ctrl:1
	v_add_f32_dpp v143, v143, v143 row_half_mirror row_mask:0xf bank_mask:0xf bound_ctrl:1
	ds_read_b128 v[56:59], v124 offset:40464
	ds_read_b32 v0, v135 offset:41216
	ds_read_b128 v[64:67], v124 offset:40704
	ds_read_b128 v[60:63], v124 offset:40720
	ds_read_b128 v[48:51], v124 offset:39936
	ds_read_b128 v[40:43], v124 offset:39952
	v_pk_mul_f32 v[182:183], v[182:183], v[142:143] op_sel_hi:[1,0]
	v_pk_mul_f32 v[184:185], v[184:185], v[142:143] op_sel_hi:[1,0]
	s_mov_b32 vcc_lo, 0x1010101
	v_pk_mul_f32 v[186:187], v[186:187], v[142:143] op_sel_hi:[1,0]
	v_pk_mul_f32 v[188:189], v[188:189], v[142:143] op_sel_hi:[1,0]
	s_mov_b32 vcc_hi, 0x1010101
	v_pk_fma_f32 v[190:191], v[190:191], v[160:161], v[182:183] op_sel_hi:[1,0,1] neg_lo:[0,0,1] neg_hi:[0,0,1]
	v_pk_fma_f32 v[192:193], v[192:193], v[160:161], v[184:185] op_sel_hi:[1,0,1] neg_lo:[0,0,1] neg_hi:[0,0,1]
	v_cndmask_b32_e32 v131, v131, v143, vcc
	v_pk_fma_f32 v[194:195], v[194:195], v[160:161], v[186:187] op_sel_hi:[1,0,1] neg_lo:[0,0,1] neg_hi:[0,0,1]
	v_pk_fma_f32 v[196:197], v[196:197], v[160:161], v[188:189] op_sel_hi:[1,0,1] neg_lo:[0,0,1] neg_hi:[0,0,1]
	ds_read_b128 v[52:55], v124 offset:40976
	ds_read_b128 v[44:47], v124 offset:40960
	v_pk_fma_f32 v[36:37], v[36:37], v[144:145], v[190:191]
	v_pk_fma_f32 v[38:39], v[38:39], v[146:147], v[192:193]
	v_pk_fma_f32 v[32:33], v[32:33], v[148:149], v[194:195]
	v_pk_fma_f32 v[34:35], v[34:35], v[150:151], v[196:197]
	s_waitcnt lgkmcnt(2)
	v_pk_mul_f32 v[76:77], v[32:33], v[76:77]
	v_pk_mul_f32 v[202:203], v[32:33], v[202:203]
	v_pk_mul_f32 v[78:79], v[34:35], v[78:79]
	v_pk_mul_f32 v[204:205], v[34:35], v[204:205]
	v_pk_fma_f32 v[72:73], v[36:37], v[72:73], v[76:77]
	v_pk_fma_f32 v[198:199], v[36:37], v[198:199], v[202:203]
	v_pk_fma_f32 v[74:75], v[38:39], v[74:75], v[78:79]
	v_pk_fma_f32 v[200:201], v[38:39], v[200:201], v[204:205]
	v_pk_add_f32 v[72:73], v[72:73], v[74:75]
	v_pk_add_f32 v[198:199], v[198:199], v[200:201]
	v_add_f32_e32 v142, v72, v73
	v_add_f32_e32 v143, v198, v199
	ds_read_b128 v[156:159], v124 offset:41744
	v_add_f32_dpp v142, v142, v142 quad_perm:[1,0,3,2] row_mask:0xf bank_mask:0xf bound_ctrl:1
	v_add_f32_dpp v143, v143, v143 quad_perm:[1,0,3,2] row_mask:0xf bank_mask:0xf bound_ctrl:1
	ds_read_b128 v[152:155], v124 offset:41728
	v_add_f32_dpp v142, v142, v142 quad_perm:[2,3,0,1] row_mask:0xf bank_mask:0xf bound_ctrl:1
	v_add_f32_dpp v143, v143, v143 quad_perm:[2,3,0,1] row_mask:0xf bank_mask:0xf bound_ctrl:1
	ds_read_b128 v[182:185], v124 offset:41984
	v_add_f32_dpp v142, v142, v142 row_half_mirror row_mask:0xf bank_mask:0xf bound_ctrl:1
	v_add_f32_dpp v143, v143, v143 row_half_mirror row_mask:0xf bank_mask:0xf bound_ctrl:1
	ds_read_b128 v[186:189], v124 offset:42000
	ds_read_b32 v160, v135 offset:42752
	ds_read_b128 v[190:193], v124 offset:42240
	ds_read_b128 v[194:197], v124 offset:42256
	ds_read_b128 v[144:147], v124 offset:41472
	ds_read_b128 v[148:151], v124 offset:41488
	v_pk_mul_f32 v[68:69], v[68:69], v[142:143] op_sel_hi:[1,0]
	v_pk_mul_f32 v[70:71], v[70:71], v[142:143] op_sel_hi:[1,0]
	s_lshl_b64 vcc, vcc, 1
	v_pk_mul_f32 v[56:57], v[56:57], v[142:143] op_sel_hi:[1,0]
	v_pk_mul_f32 v[58:59], v[58:59], v[142:143] op_sel_hi:[1,0]
	v_pk_fma_f32 v[64:65], v[64:65], v[0:1], v[68:69] op_sel_hi:[1,0,1] neg_lo:[0,0,1] neg_hi:[0,0,1]
	v_pk_fma_f32 v[66:67], v[66:67], v[0:1], v[70:71] op_sel_hi:[1,0,1] neg_lo:[0,0,1] neg_hi:[0,0,1]
	v_cndmask_b32_e32 v131, v131, v143, vcc
	v_pk_fma_f32 v[60:61], v[60:61], v[0:1], v[56:57] op_sel_hi:[1,0,1] neg_lo:[0,0,1] neg_hi:[0,0,1]
	v_pk_fma_f32 v[62:63], v[62:63], v[0:1], v[58:59] op_sel_hi:[1,0,1] neg_lo:[0,0,1] neg_hi:[0,0,1]
	ds_read_b128 v[202:205], v124 offset:42512
	ds_read_b128 v[198:201], v124 offset:42496
	v_pk_fma_f32 v[36:37], v[36:37], v[48:49], v[64:65]
	v_pk_fma_f32 v[38:39], v[38:39], v[50:51], v[66:67]
	v_pk_fma_f32 v[32:33], v[32:33], v[40:41], v[60:61]
	v_pk_fma_f32 v[34:35], v[34:35], v[42:43], v[62:63]
	s_waitcnt lgkmcnt(2)
	v_pk_mul_f32 v[156:157], v[32:33], v[156:157]
	v_pk_mul_f32 v[52:53], v[32:33], v[52:53]
	v_pk_mul_f32 v[158:159], v[34:35], v[158:159]
	v_pk_mul_f32 v[54:55], v[34:35], v[54:55]
	v_pk_fma_f32 v[152:153], v[36:37], v[152:153], v[156:157]
	v_pk_fma_f32 v[44:45], v[36:37], v[44:45], v[52:53]
	v_pk_fma_f32 v[154:155], v[38:39], v[154:155], v[158:159]
	v_pk_fma_f32 v[46:47], v[38:39], v[46:47], v[54:55]
	v_pk_add_f32 v[152:153], v[152:153], v[154:155]
	v_pk_add_f32 v[44:45], v[44:45], v[46:47]
	v_add_f32_e32 v142, v152, v153
	v_add_f32_e32 v143, v44, v45
	ds_read_b128 v[76:79], v124 offset:43280
	v_add_f32_dpp v142, v142, v142 quad_perm:[1,0,3,2] row_mask:0xf bank_mask:0xf bound_ctrl:1
	v_add_f32_dpp v143, v143, v143 quad_perm:[1,0,3,2] row_mask:0xf bank_mask:0xf bound_ctrl:1
	ds_read_b128 v[72:75], v124 offset:43264
	v_add_f32_dpp v142, v142, v142 quad_perm:[2,3,0,1] row_mask:0xf bank_mask:0xf bound_ctrl:1
	v_add_f32_dpp v143, v143, v143 quad_perm:[2,3,0,1] row_mask:0xf bank_mask:0xf bound_ctrl:1
	ds_read_b128 v[68:71], v124 offset:43520
	v_add_f32_dpp v142, v142, v142 row_half_mirror row_mask:0xf bank_mask:0xf bound_ctrl:1
	v_add_f32_dpp v143, v143, v143 row_half_mirror row_mask:0xf bank_mask:0xf bound_ctrl:1
	ds_read_b128 v[56:59], v124 offset:43536
	ds_read_b32 v0, v135 offset:44288
	ds_read_b128 v[64:67], v124 offset:43776
	ds_read_b128 v[60:63], v124 offset:43792
	ds_read_b128 v[48:51], v124 offset:43008
	ds_read_b128 v[40:43], v124 offset:43024
	v_pk_mul_f32 v[182:183], v[182:183], v[142:143] op_sel_hi:[1,0]
	v_pk_mul_f32 v[184:185], v[184:185], v[142:143] op_sel_hi:[1,0]
	s_lshl_b64 vcc, vcc, 1
	v_pk_mul_f32 v[186:187], v[186:187], v[142:143] op_sel_hi:[1,0]
	v_pk_mul_f32 v[188:189], v[188:189], v[142:143] op_sel_hi:[1,0]
	v_pk_fma_f32 v[190:191], v[190:191], v[160:161], v[182:183] op_sel_hi:[1,0,1] neg_lo:[0,0,1] neg_hi:[0,0,1]
	v_pk_fma_f32 v[192:193], v[192:193], v[160:161], v[184:185] op_sel_hi:[1,0,1] neg_lo:[0,0,1] neg_hi:[0,0,1]
	v_cndmask_b32_e32 v131, v131, v143, vcc
	v_pk_fma_f32 v[194:195], v[194:195], v[160:161], v[186:187] op_sel_hi:[1,0,1] neg_lo:[0,0,1] neg_hi:[0,0,1]
	v_pk_fma_f32 v[196:197], v[196:197], v[160:161], v[188:189] op_sel_hi:[1,0,1] neg_lo:[0,0,1] neg_hi:[0,0,1]
	ds_read_b128 v[52:55], v124 offset:44048
	ds_read_b128 v[44:47], v124 offset:44032
	v_pk_fma_f32 v[36:37], v[36:37], v[144:145], v[190:191]
	v_pk_fma_f32 v[38:39], v[38:39], v[146:147], v[192:193]
	v_pk_fma_f32 v[32:33], v[32:33], v[148:149], v[194:195]
	v_pk_fma_f32 v[34:35], v[34:35], v[150:151], v[196:197]
	s_waitcnt lgkmcnt(2)
	v_pk_mul_f32 v[76:77], v[32:33], v[76:77]
	v_pk_mul_f32 v[202:203], v[32:33], v[202:203]
	v_pk_mul_f32 v[78:79], v[34:35], v[78:79]
	v_pk_mul_f32 v[204:205], v[34:35], v[204:205]
	v_pk_fma_f32 v[72:73], v[36:37], v[72:73], v[76:77]
	v_pk_fma_f32 v[198:199], v[36:37], v[198:199], v[202:203]
	v_pk_fma_f32 v[74:75], v[38:39], v[74:75], v[78:79]
	v_pk_fma_f32 v[200:201], v[38:39], v[200:201], v[204:205]
	v_pk_add_f32 v[72:73], v[72:73], v[74:75]
	v_pk_add_f32 v[198:199], v[198:199], v[200:201]
	v_add_f32_e32 v142, v72, v73
	v_add_f32_e32 v143, v198, v199
	ds_read_b128 v[156:159], v124 offset:44816
	v_add_f32_dpp v142, v142, v142 quad_perm:[1,0,3,2] row_mask:0xf bank_mask:0xf bound_ctrl:1
	v_add_f32_dpp v143, v143, v143 quad_perm:[1,0,3,2] row_mask:0xf bank_mask:0xf bound_ctrl:1
	ds_read_b128 v[152:155], v124 offset:44800
	v_add_f32_dpp v142, v142, v142 quad_perm:[2,3,0,1] row_mask:0xf bank_mask:0xf bound_ctrl:1
	v_add_f32_dpp v143, v143, v143 quad_perm:[2,3,0,1] row_mask:0xf bank_mask:0xf bound_ctrl:1
	ds_read_b128 v[182:185], v124 offset:45056
	v_add_f32_dpp v142, v142, v142 row_half_mirror row_mask:0xf bank_mask:0xf bound_ctrl:1
	v_add_f32_dpp v143, v143, v143 row_half_mirror row_mask:0xf bank_mask:0xf bound_ctrl:1
	ds_read_b128 v[186:189], v124 offset:45072
	ds_read_b32 v160, v135 offset:45824
	ds_read_b128 v[190:193], v124 offset:45312
	ds_read_b128 v[194:197], v124 offset:45328
	ds_read_b128 v[144:147], v124 offset:44544
	ds_read_b128 v[148:151], v124 offset:44560
	v_pk_mul_f32 v[68:69], v[68:69], v[142:143] op_sel_hi:[1,0]
	v_pk_mul_f32 v[70:71], v[70:71], v[142:143] op_sel_hi:[1,0]
	s_lshl_b64 vcc, vcc, 1
	v_pk_mul_f32 v[56:57], v[56:57], v[142:143] op_sel_hi:[1,0]
	v_pk_mul_f32 v[58:59], v[58:59], v[142:143] op_sel_hi:[1,0]
	v_pk_fma_f32 v[64:65], v[64:65], v[0:1], v[68:69] op_sel_hi:[1,0,1] neg_lo:[0,0,1] neg_hi:[0,0,1]
	v_pk_fma_f32 v[66:67], v[66:67], v[0:1], v[70:71] op_sel_hi:[1,0,1] neg_lo:[0,0,1] neg_hi:[0,0,1]
	v_cndmask_b32_e32 v131, v131, v143, vcc
	v_pk_fma_f32 v[60:61], v[60:61], v[0:1], v[56:57] op_sel_hi:[1,0,1] neg_lo:[0,0,1] neg_hi:[0,0,1]
	v_pk_fma_f32 v[62:63], v[62:63], v[0:1], v[58:59] op_sel_hi:[1,0,1] neg_lo:[0,0,1] neg_hi:[0,0,1]
	ds_read_b128 v[202:205], v124 offset:45584
	ds_read_b128 v[198:201], v124 offset:45568
	v_pk_fma_f32 v[36:37], v[36:37], v[48:49], v[64:65]
	v_pk_fma_f32 v[38:39], v[38:39], v[50:51], v[66:67]
	v_pk_fma_f32 v[32:33], v[32:33], v[40:41], v[60:61]
	v_pk_fma_f32 v[34:35], v[34:35], v[42:43], v[62:63]
	s_waitcnt lgkmcnt(2)
	v_pk_mul_f32 v[156:157], v[32:33], v[156:157]
	v_pk_mul_f32 v[52:53], v[32:33], v[52:53]
	v_pk_mul_f32 v[158:159], v[34:35], v[158:159]
	v_pk_mul_f32 v[54:55], v[34:35], v[54:55]
	v_pk_fma_f32 v[152:153], v[36:37], v[152:153], v[156:157]
	v_pk_fma_f32 v[44:45], v[36:37], v[44:45], v[52:53]
	v_pk_fma_f32 v[154:155], v[38:39], v[154:155], v[158:159]
	v_pk_fma_f32 v[46:47], v[38:39], v[46:47], v[54:55]
	v_pk_add_f32 v[152:153], v[152:153], v[154:155]
	v_pk_add_f32 v[44:45], v[44:45], v[46:47]
	v_add_f32_e32 v142, v152, v153
	v_add_f32_e32 v143, v44, v45
	ds_read_b128 v[76:79], v124 offset:46352
	v_add_f32_dpp v142, v142, v142 quad_perm:[1,0,3,2] row_mask:0xf bank_mask:0xf bound_ctrl:1
	v_add_f32_dpp v143, v143, v143 quad_perm:[1,0,3,2] row_mask:0xf bank_mask:0xf bound_ctrl:1
	ds_read_b128 v[72:75], v124 offset:46336
	v_add_f32_dpp v142, v142, v142 quad_perm:[2,3,0,1] row_mask:0xf bank_mask:0xf bound_ctrl:1
	v_add_f32_dpp v143, v143, v143 quad_perm:[2,3,0,1] row_mask:0xf bank_mask:0xf bound_ctrl:1
	ds_read_b128 v[68:71], v124 offset:46592
	v_add_f32_dpp v142, v142, v142 row_half_mirror row_mask:0xf bank_mask:0xf bound_ctrl:1
	v_add_f32_dpp v143, v143, v143 row_half_mirror row_mask:0xf bank_mask:0xf bound_ctrl:1
	ds_read_b128 v[56:59], v124 offset:46608
	ds_read_b32 v0, v135 offset:47360
	ds_read_b128 v[64:67], v124 offset:46848
	ds_read_b128 v[60:63], v124 offset:46864
	ds_read_b128 v[48:51], v124 offset:46080
	ds_read_b128 v[40:43], v124 offset:46096
	v_pk_mul_f32 v[182:183], v[182:183], v[142:143] op_sel_hi:[1,0]
	v_pk_mul_f32 v[184:185], v[184:185], v[142:143] op_sel_hi:[1,0]
	s_lshl_b64 vcc, vcc, 1
	v_pk_mul_f32 v[186:187], v[186:187], v[142:143] op_sel_hi:[1,0]
	v_pk_mul_f32 v[188:189], v[188:189], v[142:143] op_sel_hi:[1,0]
	v_pk_fma_f32 v[190:191], v[190:191], v[160:161], v[182:183] op_sel_hi:[1,0,1] neg_lo:[0,0,1] neg_hi:[0,0,1]
	v_pk_fma_f32 v[192:193], v[192:193], v[160:161], v[184:185] op_sel_hi:[1,0,1] neg_lo:[0,0,1] neg_hi:[0,0,1]
	v_cndmask_b32_e32 v131, v131, v143, vcc
	v_pk_fma_f32 v[194:195], v[194:195], v[160:161], v[186:187] op_sel_hi:[1,0,1] neg_lo:[0,0,1] neg_hi:[0,0,1]
	v_pk_fma_f32 v[196:197], v[196:197], v[160:161], v[188:189] op_sel_hi:[1,0,1] neg_lo:[0,0,1] neg_hi:[0,0,1]
	ds_read_b128 v[52:55], v124 offset:47120
	ds_read_b128 v[44:47], v124 offset:47104
	v_pk_fma_f32 v[36:37], v[36:37], v[144:145], v[190:191]
	v_pk_fma_f32 v[38:39], v[38:39], v[146:147], v[192:193]
	v_pk_fma_f32 v[32:33], v[32:33], v[148:149], v[194:195]
	v_pk_fma_f32 v[34:35], v[34:35], v[150:151], v[196:197]
	s_waitcnt lgkmcnt(2)
	v_pk_mul_f32 v[76:77], v[32:33], v[76:77]
	v_pk_mul_f32 v[202:203], v[32:33], v[202:203]
	v_pk_mul_f32 v[78:79], v[34:35], v[78:79]
	v_pk_mul_f32 v[204:205], v[34:35], v[204:205]
	v_pk_fma_f32 v[72:73], v[36:37], v[72:73], v[76:77]
	v_pk_fma_f32 v[198:199], v[36:37], v[198:199], v[202:203]
	v_pk_fma_f32 v[74:75], v[38:39], v[74:75], v[78:79]
	v_pk_fma_f32 v[200:201], v[38:39], v[200:201], v[204:205]
	v_pk_add_f32 v[72:73], v[72:73], v[74:75]
	v_pk_add_f32 v[198:199], v[198:199], v[200:201]
	v_add_f32_e32 v142, v72, v73
	v_add_f32_e32 v143, v198, v199
	ds_read_b128 v[156:159], v124 offset:47888
	v_add_f32_dpp v142, v142, v142 quad_perm:[1,0,3,2] row_mask:0xf bank_mask:0xf bound_ctrl:1
	v_add_f32_dpp v143, v143, v143 quad_perm:[1,0,3,2] row_mask:0xf bank_mask:0xf bound_ctrl:1
	ds_read_b128 v[152:155], v124 offset:47872
	v_add_f32_dpp v142, v142, v142 quad_perm:[2,3,0,1] row_mask:0xf bank_mask:0xf bound_ctrl:1
	v_add_f32_dpp v143, v143, v143 quad_perm:[2,3,0,1] row_mask:0xf bank_mask:0xf bound_ctrl:1
	ds_read_b128 v[182:185], v124 offset:48128
	v_add_f32_dpp v142, v142, v142 row_half_mirror row_mask:0xf bank_mask:0xf bound_ctrl:1
	v_add_f32_dpp v143, v143, v143 row_half_mirror row_mask:0xf bank_mask:0xf bound_ctrl:1
	ds_read_b128 v[186:189], v124 offset:48144
	ds_read_b32 v160, v135 offset:48896
	ds_read_b128 v[190:193], v124 offset:48384
	ds_read_b128 v[194:197], v124 offset:48400
	ds_read_b128 v[144:147], v124 offset:47616
	ds_read_b128 v[148:151], v124 offset:47632
	v_pk_mul_f32 v[68:69], v[68:69], v[142:143] op_sel_hi:[1,0]
	v_pk_mul_f32 v[70:71], v[70:71], v[142:143] op_sel_hi:[1,0]
	s_lshl_b64 vcc, vcc, 1
	v_pk_mul_f32 v[56:57], v[56:57], v[142:143] op_sel_hi:[1,0]
	v_pk_mul_f32 v[58:59], v[58:59], v[142:143] op_sel_hi:[1,0]
	v_pk_fma_f32 v[64:65], v[64:65], v[0:1], v[68:69] op_sel_hi:[1,0,1] neg_lo:[0,0,1] neg_hi:[0,0,1]
	v_pk_fma_f32 v[66:67], v[66:67], v[0:1], v[70:71] op_sel_hi:[1,0,1] neg_lo:[0,0,1] neg_hi:[0,0,1]
	v_cndmask_b32_e32 v131, v131, v143, vcc
	v_pk_fma_f32 v[60:61], v[60:61], v[0:1], v[56:57] op_sel_hi:[1,0,1] neg_lo:[0,0,1] neg_hi:[0,0,1]
	v_pk_fma_f32 v[62:63], v[62:63], v[0:1], v[58:59] op_sel_hi:[1,0,1] neg_lo:[0,0,1] neg_hi:[0,0,1]
	ds_read_b128 v[202:205], v124 offset:48656
	ds_read_b128 v[198:201], v124 offset:48640
	v_pk_fma_f32 v[36:37], v[36:37], v[48:49], v[64:65]
	v_pk_fma_f32 v[38:39], v[38:39], v[50:51], v[66:67]
	v_pk_fma_f32 v[32:33], v[32:33], v[40:41], v[60:61]
	v_pk_fma_f32 v[34:35], v[34:35], v[42:43], v[62:63]
	s_waitcnt lgkmcnt(2)
	v_pk_mul_f32 v[156:157], v[32:33], v[156:157]
	v_pk_mul_f32 v[52:53], v[32:33], v[52:53]
	v_pk_mul_f32 v[158:159], v[34:35], v[158:159]
	v_pk_mul_f32 v[54:55], v[34:35], v[54:55]
	v_pk_fma_f32 v[152:153], v[36:37], v[152:153], v[156:157]
	v_pk_fma_f32 v[44:45], v[36:37], v[44:45], v[52:53]
	v_pk_fma_f32 v[154:155], v[38:39], v[154:155], v[158:159]
	v_pk_fma_f32 v[46:47], v[38:39], v[46:47], v[54:55]
	v_pk_add_f32 v[152:153], v[152:153], v[154:155]
	v_pk_add_f32 v[44:45], v[44:45], v[46:47]
	v_add_f32_e32 v142, v152, v153
	v_add_f32_e32 v143, v44, v45
	s_nop 0
	v_add_f32_dpp v142, v142, v142 quad_perm:[1,0,3,2] row_mask:0xf bank_mask:0xf bound_ctrl:1
	v_add_f32_dpp v143, v143, v143 quad_perm:[1,0,3,2] row_mask:0xf bank_mask:0xf bound_ctrl:1
	s_nop 0
	v_add_f32_dpp v142, v142, v142 quad_perm:[2,3,0,1] row_mask:0xf bank_mask:0xf bound_ctrl:1
	v_add_f32_dpp v143, v143, v143 quad_perm:[2,3,0,1] row_mask:0xf bank_mask:0xf bound_ctrl:1
	s_nop 0
	v_add_f32_dpp v142, v142, v142 row_half_mirror row_mask:0xf bank_mask:0xf bound_ctrl:1
	v_add_f32_dpp v143, v143, v143 row_half_mirror row_mask:0xf bank_mask:0xf bound_ctrl:1
	v_pk_mul_f32 v[182:183], v[182:183], v[142:143] op_sel_hi:[1,0]
	v_pk_mul_f32 v[184:185], v[184:185], v[142:143] op_sel_hi:[1,0]
	s_lshl_b64 vcc, vcc, 1
	v_pk_mul_f32 v[186:187], v[186:187], v[142:143] op_sel_hi:[1,0]
	v_pk_mul_f32 v[188:189], v[188:189], v[142:143] op_sel_hi:[1,0]
	v_pk_fma_f32 v[190:191], v[190:191], v[160:161], v[182:183] op_sel_hi:[1,0,1] neg_lo:[0,0,1] neg_hi:[0,0,1]
	v_pk_fma_f32 v[192:193], v[192:193], v[160:161], v[184:185] op_sel_hi:[1,0,1] neg_lo:[0,0,1] neg_hi:[0,0,1]
	v_cndmask_b32_e32 v131, v131, v143, vcc
	v_pk_fma_f32 v[194:195], v[194:195], v[160:161], v[186:187] op_sel_hi:[1,0,1] neg_lo:[0,0,1] neg_hi:[0,0,1]
	v_pk_fma_f32 v[196:197], v[196:197], v[160:161], v[188:189] op_sel_hi:[1,0,1] neg_lo:[0,0,1] neg_hi:[0,0,1]
	v_pk_fma_f32 v[36:37], v[36:37], v[144:145], v[190:191]
	v_pk_fma_f32 v[38:39], v[38:39], v[146:147], v[192:193]
	v_pk_fma_f32 v[32:33], v[32:33], v[148:149], v[194:195]
	v_pk_fma_f32 v[34:35], v[34:35], v[150:151], v[196:197]
	s_waitcnt lgkmcnt(0)
	v_pk_mul_f32 v[202:203], v[32:33], v[202:203]
	v_pk_mul_f32 v[204:205], v[34:35], v[204:205]
	v_pk_fma_f32 v[198:199], v[36:37], v[198:199], v[202:203]
	v_pk_fma_f32 v[200:201], v[38:39], v[200:201], v[204:205]
	v_pk_add_f32 v[198:199], v[198:199], v[200:201]
	v_add_f32_e32 v143, v198, v199
	s_nop 1
	v_add_f32_dpp v143, v143, v143 quad_perm:[1,0,3,2] row_mask:0xf bank_mask:0xf bound_ctrl:1
	s_nop 1
	v_add_f32_dpp v143, v143, v143 quad_perm:[2,3,0,1] row_mask:0xf bank_mask:0xf bound_ctrl:1
	s_nop 1
	v_add_f32_dpp v143, v143, v143 row_half_mirror row_mask:0xf bank_mask:0xf bound_ctrl:1
	s_lshl_b64 vcc, vcc, 1
	v_cndmask_b32_e32 v131, v131, v143, vcc
	s_setprio 0
	s_add_i32 s70, s64, 1
	s_cmp_eq_u32 s70, s84
	s_cbranch_scc1 .Lrw_epi_last
	s_and_b32 s70, s64, 1
	s_mul_i32 s70, s70, 0x1200
	s_add_u32 s70, s70, 0x19000
	v_mad_u32_u24 v40, v86, 36, v81
	v_lshl_add_u32 v40, v40, 2, s70
	ds_write_b32 v40, v134
	ds_write_b32 v40, v133 offset:1152
	ds_write_b32 v40, v132 offset:2304
	ds_write_b32 v40, v131 offset:3456
	s_mov_b64 s[20:21], 0
	s_branch .LBB0_654
.Lrw_epi_last:
	s_lshl_b32 s70, s64, 5
	s_add_u32 s70, s70, s4
	v_add_u32_e32 v40, s70, v86
	v_lshlrev_b32_e32 v46, 1, v112
	v_mul_u32_u24_e32 v41, 0xc00, v40
	v_add_u32_e32 v41, v41, v46
	v_bfe_u32 v47, v134, 16, 1
	v_add3_u32 v47, v134, v47, s78
	global_store_short_d16_hi v41, v47, s[60:61]
	v_bfe_u32 v47, v133, 16, 1
	v_add3_u32 v47, v133, v47, s78
	v_add_u32_e32 v45, 0x6000, v41
	global_store_short_d16_hi v45, v47, s[60:61]
	v_bfe_u32 v47, v132, 16, 1
	v_add3_u32 v47, v132, v47, s78
	v_add_u32_e32 v45, 0xc000, v41
	global_store_short_d16_hi v45, v47, s[60:61]
	v_bfe_u32 v47, v131, 16, 1
	v_add3_u32 v47, v131, v47, s78
	v_add_u32_e32 v45, 0x12000, v41
	global_store_short_d16_hi v45, v47, s[60:61]
	s_mov_b64 s[20:21], 0
	s_branch .LBB0_654
